# retention: K/V LDS tiles in XOR-swizzled 256B-row layout (no bank conflicts on transposed reads), inner-product loop pipelined too
# speedup vs baseline: 1.0175x; 1.0175x over previous
.LBB0_884:
	s_cmp_lt_i32 s90, 11
	s_cselect_b64 s[0:1], -1, 0
	s_and_b64 s[2:3], s[0:1], s[2:3]
	s_andn2_b64 vcc, exec, s[2:3]
	s_cbranch_vccnz .LBB0_1005
	v_mov_b32_e32 v0, v248
	s_cmpk_gt_i32 s81, 0x1ff
	s_cbranch_scc1 .LBB0_1005
	s_add_u32 s60, s88, 0xd000000
	s_addc_u32 s61, s89, 0
	s_add_u32 s62, s88, 0x16000000
	s_addc_u32 s63, s89, 0
	s_add_u32 s64, s88, 0x1f000000
	s_addc_u32 s65, s89, 0
	s_add_u32 s66, s88, 0x3c00000
	s_addc_u32 s67, s89, 0
	s_waitcnt lgkmcnt(0)
	v_and_b32_e32 v2, 15, v0
	v_ashrrev_i32_e32 v11, 6, v0
	s_cmpk_eq_i32 s84, 0x100
	v_and_b32_e32 v193, 31, v0
	v_bfe_u32 v201, v0, 5, 1
	v_ashrrev_i32_e32 v202, 4, v0
	v_ashrrev_i32_e32 v1, 7, v0
	v_lshlrev_b32_e32 v3, 2, v0
	v_and_b32_e32 v4, 16, v0
	v_lshrrev_b32_e32 v7, 2, v0
	v_and_b32_e32 v12, 1, v11
	v_ashrrev_i32_e32 v13, 8, v0
	v_and_b32_e32 v11, 3, v11
	s_cselect_b64 s[24:25], -1, 0
	v_lshlrev_b32_e32 v0, 4, v2
	s_add_i32 s8, 0, 0x11000
	v_lshlrev_b32_e32 v6, 3, v201
	s_movk_i32 s14, 0x88
	v_add_u32_e32 v192, 0, v0
	v_add_u32_e32 v204, s8, v0
	v_lshl_or_b32 v0, v11, 5, v193
	v_mad_u32_u24 v10, v193, s14, v6
	v_mul_u32_u24_e32 v0, 0x110, v0
	s_add_i32 s2, 0, 0x19800
	v_lshlrev_b32_e32 v14, 7, v13
	v_add3_u32 v15, s2, v0, v14
	v_lshl_add_u32 v0, v10, 1, 0
	s_movk_i32 s6, 0x2200
	v_and_b32_e32 v3, 12, v3
	v_and_or_b32 v7, v7, 3, v6
	v_mad_u64_u32 v[194:195], s[6:7], v1, s6, v[0:1]
	v_or_b32_e32 v5, v3, v4
	v_mul_u32_u24_e32 v8, 0x88, v7
	s_movk_i32 s6, 0x4400
	v_lshlrev_b32_e32 v16, 1, v12
	v_mad_i32_i24 v195, v13, s6, v0
	v_add_lshl_u32 v0, v8, v5, 1
	v_lshlrev_b32_e32 v5, 6, v11
	v_add3_u32 v8, s8, v0, v5
	v_or_b32_e32 v0, 1, v16
	v_mul_u32_u24_e32 v9, 0x88, v193
	v_mul_u32_u24_e32 v10, 0x4400, v12
	v_cmp_eq_u32_e64 s[12:13], v0, v1
	v_lshlrev_b32_e32 v210, 5, v0
	v_lshlrev_b32_e32 v0, 4, v201
	v_or_b32_e32 v10, v10, v0
	v_lshlrev_b32_e32 v9, 1, v9
	v_mad_u32_u24 v4, v7, s14, v4
	v_mul_u32_u24_e32 v17, 0x2200, v11
	v_mul_i32_i24_e32 v18, 0x4400, v13
	v_lshl_or_b32 v206, v13, 2, 2
	s_movk_i32 s15, 0x1100
	v_add3_u32 v10, v10, v9, 0
	v_add_lshl_u32 v3, v4, v3, 1
	v_lshlrev_b32_e32 v203, 3, v2
	v_cmp_le_i32_e64 s[2:3], v16, v1
	v_cmp_lt_i32_e64 s[4:5], v16, v1
	v_lshlrev_b32_e32 v205, 5, v1
	v_cmp_eq_u32_e64 s[8:9], 0, v2
	v_cmp_eq_u32_e64 s[10:11], v16, v1
	v_mul_lo_u32 v1, v206, s15
	v_lshlrev_b32_e32 v2, 5, v206
	v_or_b32_e32 v11, 0x60, v14
	v_add_u32_e32 v211, 0x8800, v10
	v_or_b32_e32 v10, v17, v0
	v_add_u32_e32 v214, v5, v3
	v_or_b32_e32 v0, v18, v0
	s_mov_b32 s29, 0
	s_movk_i32 s68, 0x110
	v_cmp_lt_i32_e64 s[6:7], -1, v13
	v_lshlrev_b32_e32 v207, 6, v13
	v_add_u32_e32 v208, 0, v5
	v_lshlrev_b32_e32 v209, 6, v12
	v_add3_u32 v212, v10, v9, 0
	v_add3_u32 v213, v14, v3, 0
	v_add_u32_e32 v215, 0, v214
	v_add_u32_e32 v216, v0, v9
	v_mov_b32_e32 v0, 0
	s_mov_b32 s69, 0x3f2aaaab
	v_mov_b32_e32 v217, 0x3ecc95a3
	s_mov_b32 s70, 0x3f317218
	s_mov_b32 s71, 0x7f800000
	s_mov_b32 s72, 0x33800000
	s_mov_b32 s73, 0xc2fc0000
	v_add_u32_e32 v218, v8, v1
	v_add_u32_e32 v219, v195, v2
	v_add_u32_e32 v220, v195, v11
	v_mov_b32_e32 v221, 0x7f800000
	v_mov_b32_e32 v222, 0x7fc00000
	v_mov_b32_e32 v223, 0xff800000
	v_mov_b32_e32 v224, 0x42800000
	v_add_u32_e32 v225, v15, v6
	v_mbcnt_lo_u32_b32 v226, -1, 0
	s_mov_b32 s74, s81
	v_lshrrev_b32_e32 v2, 4, v248
	v_and_b32_e32 v3, 15, v248
	v_and_b32_e32 v4, 3, v2
	v_bfe_u32 v5, v2, 2, 2
	v_lshl_or_b32 v4, v4, 2, v5
	v_xor_b32_e32 v3, v3, v4
	v_lshlrev_b32_e32 v3, 4, v3
	v_lshl_or_b32 v249, v2, 8, v3
	v_and_b32_e32 v2, 31, v248
	v_bfe_u32 v3, v248, 5, 1
	v_and_b32_e32 v4, 3, v2
	v_bfe_u32 v5, v2, 2, 2
	v_lshl_or_b32 v4, v4, 2, v5
	v_xor_b32_e32 v4, v4, v3
	v_lshlrev_b32_e32 v4, 4, v4
	v_bfe_u32 v5, v248, 6, 1
	v_lshl_or_b32 v5, v5, 6, v2
	v_lshl_or_b32 v4, v5, 8, v4
	v_add_u32_e32 v250, 0x8800, v4
	v_bfe_u32 v2, v248, 5, 1
	v_bfe_u32 v3, v248, 2, 2
	v_bfe_u32 v4, v248, 4, 1
	v_and_b32_e32 v5, 3, v248
	v_lshrrev_b32_e32 v6, 1, v5
	v_lshl_or_b32 v6, v4, 1, v6
	v_and_b32_e32 v5, 1, v5
	v_lshlrev_b32_e32 v5, 3, v5
	v_lshlrev_b32_e32 v7, 1, v2
	v_xor_b32_e32 v8, v6, v7
	v_or_b32_e32 v7, 1, v7
	v_xor_b32_e32 v9, v6, v7
	v_lshl_or_b32 v8, v8, 4, v5
	v_lshl_or_b32 v9, v9, 4, v5
	v_lshl_or_b32 v2, v2, 3, v3
	v_lshl_add_u32 v8, v2, 8, v8
	v_lshl_add_u32 v9, v2, 8, v9
	v_add_u32_e32 v9, 0x400, v9
	v_lshrrev_b32_e32 v4, 8, v248
	v_lshlrev_b32_e32 v4, 1, v4
	v_xor_b32_e32 v6, v4, v3
	v_or_b32_e32 v4, 1, v4
	v_xor_b32_e32 v7, v4, v3
	v_bfe_u32 v4, v248, 6, 2
	v_xor_b32_e32 v4, v4, v3
	v_lshlrev_b32_e32 v6, 6, v6
	v_lshlrev_b32_e32 v7, 6, v7
	v_lshlrev_b32_e32 v4, 6, v4
	v_add_u32_e32 v10, 0x8800, v8
	v_add_u32_e32 v11, 0x8800, v9
	v_add_u32_e32 v12, 0x11000, v8
	v_add_u32_e32 v13, 0x11000, v9
	v_add_u32_e32 v251, v10, v6
	v_add_u32_e32 v252, v11, v6
	v_add_u32_e32 v253, v10, v7
	v_add_u32_e32 v200, v11, v7
	v_add_u32_e32 v235, v12, v4
	v_add_u32_e32 v255, v13, v4
	s_branch .LBB0_888

.LBB0_898:
	v_add_u32_e32 v1, 1, v197
	v_cvt_f32_i32_e32 v1, v1
	v_mul_lo_u32 v6, v197, s68
	s_waitcnt vmcnt(3) lgkmcnt(0)
	v_lshlrev_b32_e32 v2, 16, v160
	v_and_b32_e32 v3, 0xffff0000, v160
	v_mul_f32_e64 v1, -v232, v1
	v_exp_f32_e32 v1, v1
	v_add_u32_e32 v228, v192, v6
	ds_write_b128 v249, v[184:187] offset:34816
	v_and_b32_e32 v4, 0xffff0000, v161
	v_mul_f32_e32 v1, 0x3d800000, v1
	v_mul_f32_e32 v2, v1, v2
	v_mul_f32_e32 v3, v1, v3
	v_cvt_pk_bf16_f32 v2, v2, v3
	v_lshlrev_b32_e32 v3, 16, v161
	v_mul_f32_e32 v3, v1, v3
	v_mul_f32_e32 v4, v1, v4
	v_cvt_pk_bf16_f32 v3, v3, v4
	v_lshlrev_b32_e32 v4, 16, v162
	v_and_b32_e32 v5, 0xffff0000, v162
	v_mul_f32_e32 v4, v1, v4
	v_mul_f32_e32 v5, v1, v5
	v_cvt_pk_bf16_f32 v4, v4, v5
	v_lshlrev_b32_e32 v5, 16, v163
	v_and_b32_e32 v7, 0xffff0000, v163
	v_mul_f32_e32 v5, v1, v5
	v_mul_f32_e32 v1, v1, v7
	v_cvt_pk_bf16_f32 v5, v5, v1
	v_add_u32_e32 v1, 0x11000, v249
	ds_write_b128 v1, v[2:5]
	v_cndmask_b32_e64 v2, 0, 1, s[54:55]
	v_cmp_ne_u32_e64 s[16:17], 1, v2
	s_andn2_b64 vcc, exec, s[54:55]
	v_add_u32_e32 v231, 32, v197
	s_cbranch_vccnz .LBB0_900
	v_mad_u64_u32 v[2:3], s[14:15], v231, s68, v[192:193]
	ds_write_b128 v2, v[152:155]
.LBB0_900:
	v_add_u32_e32 v2, 33, v197
	v_cvt_f32_i32_e32 v2, v2
	s_waitcnt vmcnt(2)
	v_lshlrev_b32_e32 v3, 16, v164
	v_and_b32_e32 v4, 0xffff0000, v164
	ds_write_b128 v249, v[188:191] offset:43008
	v_mul_f32_e64 v2, -v232, v2
	v_exp_f32_e32 v2, v2
	v_lshlrev_b32_e32 v5, 16, v165
	v_and_b32_e32 v7, 0xffff0000, v167
	s_and_b64 vcc, exec, s[16:17]
	v_mul_f32_e32 v6, 0x3d800000, v2
	v_mul_f32_e32 v2, v6, v3
	v_mul_f32_e32 v3, v6, v4
	v_cvt_pk_bf16_f32 v2, v2, v3
	v_and_b32_e32 v3, 0xffff0000, v165
	v_mul_f32_e32 v4, v6, v5
	v_mul_f32_e32 v3, v6, v3
	v_cvt_pk_bf16_f32 v3, v4, v3
	v_lshlrev_b32_e32 v4, 16, v166
	v_and_b32_e32 v5, 0xffff0000, v166
	v_mul_f32_e32 v4, v6, v4
	v_mul_f32_e32 v5, v6, v5
	v_cvt_pk_bf16_f32 v4, v4, v5
	v_lshlrev_b32_e32 v5, 16, v167
	v_mul_f32_e32 v5, v6, v5
	v_add_u32_e32 v230, 64, v197
	v_mul_f32_e32 v6, v6, v7
	v_cvt_pk_bf16_f32 v5, v5, v6
	ds_write_b128 v1, v[2:5] offset:8192
	s_cbranch_vccnz .LBB0_902
	v_mad_u64_u32 v[2:3], s[14:15], v230, s68, v[192:193]
	ds_write_b128 v2, v[148:151]
.LBB0_902:
	v_add_u32_e32 v2, 0x41, v197
	v_cvt_f32_i32_e32 v2, v2
	s_waitcnt vmcnt(1)
	v_lshlrev_b32_e32 v3, 16, v168
	v_and_b32_e32 v4, 0xffff0000, v168
	ds_write_b128 v249, v[180:183] offset:51200
	v_mul_f32_e64 v2, -v232, v2
	v_exp_f32_e32 v2, v2
	v_lshlrev_b32_e32 v5, 16, v169
	v_and_b32_e32 v7, 0xffff0000, v171
	s_and_b64 vcc, exec, s[16:17]
	v_mul_f32_e32 v6, 0x3d800000, v2
	v_mul_f32_e32 v2, v6, v3
	v_mul_f32_e32 v3, v6, v4
	v_cvt_pk_bf16_f32 v2, v2, v3
	v_and_b32_e32 v3, 0xffff0000, v169
	v_mul_f32_e32 v4, v6, v5
	v_mul_f32_e32 v3, v6, v3
	v_cvt_pk_bf16_f32 v3, v4, v3
	v_lshlrev_b32_e32 v4, 16, v170
	v_and_b32_e32 v5, 0xffff0000, v170
	v_mul_f32_e32 v4, v6, v4
	v_mul_f32_e32 v5, v6, v5
	v_cvt_pk_bf16_f32 v4, v4, v5
	v_lshlrev_b32_e32 v5, 16, v171
	v_mul_f32_e32 v5, v6, v5
	v_add_u32_e32 v229, 0x60, v197
	v_mul_f32_e32 v6, v6, v7
	v_cvt_pk_bf16_f32 v5, v5, v6
	ds_write_b128 v1, v[2:5] offset:16384
	s_cbranch_vccnz .LBB0_904
	v_mad_u64_u32 v[2:3], s[14:15], v229, s68, v[192:193]
	ds_write_b128 v2, v[144:147]
.LBB0_904:
	v_add_u32_e32 v2, 0x61, v197
	v_cvt_f32_i32_e32 v2, v2
	s_waitcnt vmcnt(0)
	v_lshlrev_b32_e32 v3, 16, v172
	v_and_b32_e32 v4, 0xffff0000, v172
	ds_write_b128 v249, v[176:179] offset:59392
	v_mul_f32_e64 v2, -v232, v2
	v_exp_f32_e32 v2, v2
	v_lshlrev_b32_e32 v5, 16, v173
	v_and_b32_e32 v7, 0xffff0000, v175
	s_and_b64 vcc, exec, s[54:55]
	v_mul_f32_e32 v6, 0x3d800000, v2
	v_mul_f32_e32 v2, v6, v3
	v_mul_f32_e32 v3, v6, v4
	v_cvt_pk_bf16_f32 v2, v2, v3
	v_and_b32_e32 v3, 0xffff0000, v173
	v_mul_f32_e32 v4, v6, v5
	v_mul_f32_e32 v3, v6, v3
	v_cvt_pk_bf16_f32 v3, v4, v3
	v_lshlrev_b32_e32 v4, 16, v174
	v_and_b32_e32 v5, 0xffff0000, v174
	v_mul_f32_e32 v4, v6, v4
	v_mul_f32_e32 v5, v6, v5
	v_cvt_pk_bf16_f32 v4, v4, v5
	v_lshlrev_b32_e32 v5, 16, v175
	v_mul_f32_e32 v5, v6, v5
	s_mov_b64 s[14:15], s[30:31]
	v_mul_f32_e32 v6, v6, v7
	v_cvt_pk_bf16_f32 v5, v5, v6
	ds_write_b128 v1, v[2:5] offset:24576
	s_cbranch_vccz .LBB0_906
	v_cvt_pk_bf16_f32 v2, v64, v65
	v_cvt_pk_bf16_f32 v3, v66, v67
	ds_write_b64 v225, v[2:3]
	v_cvt_pk_bf16_f32 v2, v68, v69
	v_cvt_pk_bf16_f32 v3, v70, v71
	ds_write_b64 v225, v[2:3] offset:16
	v_cvt_pk_bf16_f32 v2, v72, v73
	v_cvt_pk_bf16_f32 v3, v74, v75
	ds_write_b64 v225, v[2:3] offset:32
	v_cvt_pk_bf16_f32 v2, v76, v77
	v_cvt_pk_bf16_f32 v3, v78, v79
	ds_write_b64 v225, v[2:3] offset:48
	v_cvt_pk_bf16_f32 v2, v48, v49
	v_cvt_pk_bf16_f32 v3, v50, v51
	ds_write_b64 v225, v[2:3] offset:64
	v_cvt_pk_bf16_f32 v2, v52, v53
	v_cvt_pk_bf16_f32 v3, v54, v55
	ds_write_b64 v225, v[2:3] offset:80
	v_cvt_pk_bf16_f32 v2, v56, v57
	v_cvt_pk_bf16_f32 v3, v58, v59
	s_mov_b64 s[14:15], s[40:41]
	ds_write_b64 v225, v[2:3] offset:96
	v_cvt_pk_bf16_f32 v2, v60, v61
	v_cvt_pk_bf16_f32 v3, v62, v63
	ds_write_b64 v225, v[2:3] offset:112

.LBB0_914:
	v_lshl_add_u64 v[2:3], v[2:3], 1, s[18:19]
	global_load_dwordx4 v[176:179], v[2:3], off offset:256
	s_and_b64 vcc, exec, s[16:17]
	s_mov_b32 s33, 0
	s_waitcnt lgkmcnt(0)
	s_barrier
	v_sub_co_u32_e64 v1, s[14:15], s49, 1
	s_cbranch_vccnz .Lret_b0_ctx
	v_mov_b32_e32 v80, 0
	v_mov_b32_e32 v81, 0
	v_mov_b32_e32 v82, 0
	v_mov_b32_e32 v83, 0
	v_mov_b32_e32 v84, 0
	v_mov_b32_e32 v85, 0
	v_mov_b32_e32 v86, 0
	v_mov_b32_e32 v87, 0
	v_mov_b32_e32 v88, 0
	v_mov_b32_e32 v89, 0
	v_mov_b32_e32 v90, 0
	v_mov_b32_e32 v91, 0
	v_mov_b32_e32 v92, 0
	v_mov_b32_e32 v93, 0
	v_mov_b32_e32 v94, 0
	v_mov_b32_e32 v95, 0
	v_mov_b32_e32 v96, 0
	v_mov_b32_e32 v97, 0
	v_mov_b32_e32 v98, 0
	v_mov_b32_e32 v99, 0
	v_mov_b32_e32 v100, 0
	v_mov_b32_e32 v101, 0
	v_mov_b32_e32 v102, 0
	v_mov_b32_e32 v103, 0
	v_mov_b32_e32 v104, 0
	v_mov_b32_e32 v105, 0
	v_mov_b32_e32 v106, 0
	v_mov_b32_e32 v107, 0
	v_mov_b32_e32 v108, 0
	v_mov_b32_e32 v109, 0
	v_mov_b32_e32 v110, 0
	v_mov_b32_e32 v111, 0
	v_mov_b32_e32 v112, 0
	v_mov_b32_e32 v113, 0
	v_mov_b32_e32 v114, 0
	v_mov_b32_e32 v115, 0
	v_mov_b32_e32 v116, 0
	v_mov_b32_e32 v117, 0
	v_mov_b32_e32 v118, 0
	v_mov_b32_e32 v119, 0
	v_mov_b32_e32 v120, 0
	v_mov_b32_e32 v121, 0
	v_mov_b32_e32 v122, 0
	v_mov_b32_e32 v123, 0
	v_mov_b32_e32 v124, 0
	v_mov_b32_e32 v125, 0
	v_mov_b32_e32 v126, 0
	v_mov_b32_e32 v127, 0
	v_mov_b32_e32 v128, 0
	v_mov_b32_e32 v129, 0
	v_mov_b32_e32 v130, 0
	v_mov_b32_e32 v131, 0
	v_mov_b32_e32 v132, 0
	v_mov_b32_e32 v133, 0
	v_mov_b32_e32 v134, 0
	v_mov_b32_e32 v135, 0
	v_mov_b32_e32 v136, 0
	v_mov_b32_e32 v137, 0
	v_mov_b32_e32 v138, 0
	v_mov_b32_e32 v139, 0
	v_mov_b32_e32 v140, 0
	v_mov_b32_e32 v141, 0
	v_mov_b32_e32 v142, 0
	v_mov_b32_e32 v143, 0
	v_add_u32_e32 v14, 0x19800, v212
	s_and_b64 vcc, exec, s[2:3]
	s_cbranch_vccz .Lret_b0_c
	s_and_b64 vcc, exec, s[4:5]
	s_cbranch_vccz .Lret_b0_b
	ds_read_b128 v[2:5], v250
	ds_read_b128 v[6:9], v250 offset:8192
	ds_read_b128 v[10:13], v194
	v_xor_b32_e32 v15, 32, v250
	ds_read_b128 v[236:239], v15
	ds_read_b128 v[240:243], v15 offset:8192
	ds_read_b128 v[244:247], v194 offset:32
	v_xor_b32_e32 v15, 64, v250
	ds_read_b128 v[160:163], v15
	ds_read_b128 v[164:167], v15 offset:8192
	s_waitcnt lgkmcnt(5)
	v_mfma_f32_32x32x16_bf16 v[128:143], v[2:5], v[10:13], v[128:143]
	ds_read_b128 v[168:171], v194 offset:64
	v_mfma_f32_32x32x16_bf16 v[112:127], v[6:9], v[10:13], v[112:127]
	v_xor_b32_e32 v15, 0x60, v250
	ds_read_b128 v[2:5], v15
	ds_read_b128 v[6:9], v15 offset:8192
	s_waitcnt lgkmcnt(5)
	v_mfma_f32_32x32x16_bf16 v[128:143], v[236:239], v[244:247], v[128:143]
	ds_read_b128 v[10:13], v194 offset:96
	v_mfma_f32_32x32x16_bf16 v[112:127], v[240:243], v[244:247], v[112:127]
	v_xor_b32_e32 v15, 0x80, v250
	ds_read_b128 v[236:239], v15
	ds_read_b128 v[240:243], v15 offset:8192
	s_waitcnt lgkmcnt(5)
	v_mfma_f32_32x32x16_bf16 v[128:143], v[160:163], v[168:171], v[128:143]
	ds_read_b128 v[244:247], v194 offset:128
	v_mfma_f32_32x32x16_bf16 v[112:127], v[164:167], v[168:171], v[112:127]
	v_xor_b32_e32 v15, 0xa0, v250
	ds_read_b128 v[160:163], v15
	ds_read_b128 v[164:167], v15 offset:8192
	s_waitcnt lgkmcnt(5)
	v_mfma_f32_32x32x16_bf16 v[128:143], v[2:5], v[10:13], v[128:143]
	ds_read_b128 v[168:171], v194 offset:160
	v_mfma_f32_32x32x16_bf16 v[112:127], v[6:9], v[10:13], v[112:127]
	v_xor_b32_e32 v15, 0xc0, v250
	ds_read_b128 v[2:5], v15
	ds_read_b128 v[6:9], v15 offset:8192
	s_waitcnt lgkmcnt(5)
	v_mfma_f32_32x32x16_bf16 v[128:143], v[236:239], v[244:247], v[128:143]
	ds_read_b128 v[10:13], v194 offset:192
	v_mfma_f32_32x32x16_bf16 v[112:127], v[240:243], v[244:247], v[112:127]
	v_xor_b32_e32 v15, 0xe0, v250
	ds_read_b128 v[236:239], v15
	ds_read_b128 v[240:243], v15 offset:8192
	s_waitcnt lgkmcnt(5)
	v_mfma_f32_32x32x16_bf16 v[128:143], v[160:163], v[168:171], v[128:143]
	ds_read_b128 v[244:247], v194 offset:224
	v_mfma_f32_32x32x16_bf16 v[112:127], v[164:167], v[168:171], v[112:127]
	ds_read_b128 v[160:163], v14
	ds_read_b128 v[164:167], v195
	s_waitcnt lgkmcnt(5)
	v_mfma_f32_32x32x16_bf16 v[128:143], v[2:5], v[10:13], v[128:143]
	ds_read_b128 v[168:171], v195 offset:8704
	v_mfma_f32_32x32x16_bf16 v[112:127], v[6:9], v[10:13], v[112:127]
	ds_read_b128 v[2:5], v14 offset:32
	ds_read_b128 v[6:9], v195 offset:32
	s_waitcnt lgkmcnt(5)
	v_mfma_f32_32x32x16_bf16 v[128:143], v[236:239], v[244:247], v[128:143]
	ds_read_b128 v[10:13], v195 offset:8736
	v_mfma_f32_32x32x16_bf16 v[112:127], v[240:243], v[244:247], v[112:127]
	ds_read_b128 v[236:239], v14 offset:64
	ds_read_b128 v[240:243], v195 offset:64
	s_waitcnt lgkmcnt(5)
	v_mfma_f32_32x32x16_bf16 v[96:111], v[160:163], v[164:167], v[96:111]
	ds_read_b128 v[244:247], v195 offset:8768
	v_mfma_f32_32x32x16_bf16 v[80:95], v[160:163], v[168:171], v[80:95]
	ds_read_b128 v[160:163], v14 offset:96
	ds_read_b128 v[164:167], v195 offset:96
	s_waitcnt lgkmcnt(5)
	v_mfma_f32_32x32x16_bf16 v[96:111], v[2:5], v[6:9], v[96:111]
	ds_read_b128 v[168:171], v195 offset:8800
	v_mfma_f32_32x32x16_bf16 v[80:95], v[2:5], v[10:13], v[80:95]
	ds_read_b128 v[2:5], v14 offset:128
	ds_read_b128 v[6:9], v195 offset:128
	s_waitcnt lgkmcnt(5)
	v_mfma_f32_32x32x16_bf16 v[96:111], v[236:239], v[240:243], v[96:111]
	ds_read_b128 v[10:13], v195 offset:8832
	v_mfma_f32_32x32x16_bf16 v[80:95], v[236:239], v[244:247], v[80:95]
	ds_read_b128 v[236:239], v14 offset:160
	ds_read_b128 v[240:243], v195 offset:160
	s_waitcnt lgkmcnt(5)
	v_mfma_f32_32x32x16_bf16 v[96:111], v[160:163], v[164:167], v[96:111]
	ds_read_b128 v[244:247], v195 offset:8864
	v_mfma_f32_32x32x16_bf16 v[80:95], v[160:163], v[168:171], v[80:95]
	ds_read_b128 v[160:163], v14 offset:192
	ds_read_b128 v[164:167], v195 offset:192
	s_waitcnt lgkmcnt(5)
	v_mfma_f32_32x32x16_bf16 v[96:111], v[2:5], v[6:9], v[96:111]
	ds_read_b128 v[168:171], v195 offset:8896
	v_mfma_f32_32x32x16_bf16 v[80:95], v[2:5], v[10:13], v[80:95]
	ds_read_b128 v[2:5], v14 offset:224
	ds_read_b128 v[6:9], v195 offset:224
	s_waitcnt lgkmcnt(5)
	v_mfma_f32_32x32x16_bf16 v[96:111], v[236:239], v[240:243], v[96:111]
	ds_read_b128 v[10:13], v195 offset:8928
	v_mfma_f32_32x32x16_bf16 v[80:95], v[236:239], v[244:247], v[80:95]
	ds_read_b64_tr_b16 v[236:237], v251
	ds_read_b64_tr_b16 v[238:239], v252
	ds_read_b64_tr_b16 v[244:245], v235
	s_waitcnt lgkmcnt(6)
	v_mfma_f32_32x32x16_bf16 v[96:111], v[160:163], v[164:167], v[96:111]
	ds_read_b64_tr_b16 v[246:247], v255
	ds_read_b64_tr_b16 v[240:241], v253
	ds_read_b64_tr_b16 v[242:243], v200
	v_mfma_f32_32x32x16_bf16 v[80:95], v[160:163], v[168:171], v[80:95]
	ds_read_b64_tr_b16 v[160:161], v251 offset:4096
	ds_read_b64_tr_b16 v[162:163], v252 offset:4096
	ds_read_b64_tr_b16 v[168:169], v235 offset:4096
	s_waitcnt lgkmcnt(9)
	v_mfma_f32_32x32x16_bf16 v[96:111], v[2:5], v[6:9], v[96:111]
	ds_read_b64_tr_b16 v[170:171], v255 offset:4096
	ds_read_b64_tr_b16 v[164:165], v253 offset:4096
	ds_read_b64_tr_b16 v[166:167], v200 offset:4096
	v_mfma_f32_32x32x16_bf16 v[80:95], v[2:5], v[10:13], v[80:95]
	ds_read_b64_tr_b16 v[2:3], v251 offset:8192
	ds_read_b64_tr_b16 v[4:5], v252 offset:8192
	ds_read_b64_tr_b16 v[10:11], v235 offset:8192
	s_waitcnt lgkmcnt(9)
	v_mfma_f32_32x32x16_bf16 v[64:79], v[236:239], v[244:247], v[64:79]
	ds_read_b64_tr_b16 v[12:13], v255 offset:8192
	ds_read_b64_tr_b16 v[6:7], v253 offset:8192
	ds_read_b64_tr_b16 v[8:9], v200 offset:8192
	v_mfma_f32_32x32x16_bf16 v[48:63], v[240:243], v[244:247], v[48:63]
	ds_read_b64_tr_b16 v[236:237], v251 offset:12288
	ds_read_b64_tr_b16 v[238:239], v252 offset:12288
	ds_read_b64_tr_b16 v[244:245], v235 offset:12288
	s_waitcnt lgkmcnt(9)
	v_mfma_f32_32x32x16_bf16 v[64:79], v[160:163], v[168:171], v[64:79]
	ds_read_b64_tr_b16 v[246:247], v255 offset:12288
	ds_read_b64_tr_b16 v[240:241], v253 offset:12288
	ds_read_b64_tr_b16 v[242:243], v200 offset:12288
	v_mfma_f32_32x32x16_bf16 v[48:63], v[164:167], v[168:171], v[48:63]
	ds_read_b64_tr_b16 v[160:161], v251 offset:16384
	ds_read_b64_tr_b16 v[162:163], v252 offset:16384
	ds_read_b64_tr_b16 v[168:169], v235 offset:16384
	s_waitcnt lgkmcnt(9)
	v_mfma_f32_32x32x16_bf16 v[64:79], v[2:5], v[10:13], v[64:79]
	ds_read_b64_tr_b16 v[170:171], v255 offset:16384
	ds_read_b64_tr_b16 v[164:165], v253 offset:16384
	ds_read_b64_tr_b16 v[166:167], v200 offset:16384
	v_mfma_f32_32x32x16_bf16 v[48:63], v[6:9], v[10:13], v[48:63]
	ds_read_b64_tr_b16 v[2:3], v251 offset:20480
	ds_read_b64_tr_b16 v[4:5], v252 offset:20480
	ds_read_b64_tr_b16 v[10:11], v235 offset:20480
	s_waitcnt lgkmcnt(9)
	v_mfma_f32_32x32x16_bf16 v[64:79], v[236:239], v[244:247], v[64:79]
	ds_read_b64_tr_b16 v[12:13], v255 offset:20480
	ds_read_b64_tr_b16 v[6:7], v253 offset:20480
	ds_read_b64_tr_b16 v[8:9], v200 offset:20480
	v_mfma_f32_32x32x16_bf16 v[48:63], v[240:243], v[244:247], v[48:63]
	ds_read_b64_tr_b16 v[236:237], v251 offset:24576
	ds_read_b64_tr_b16 v[238:239], v252 offset:24576
	ds_read_b64_tr_b16 v[244:245], v235 offset:24576
	s_waitcnt lgkmcnt(9)
	v_mfma_f32_32x32x16_bf16 v[64:79], v[160:163], v[168:171], v[64:79]
	ds_read_b64_tr_b16 v[246:247], v255 offset:24576
	ds_read_b64_tr_b16 v[240:241], v253 offset:24576
	ds_read_b64_tr_b16 v[242:243], v200 offset:24576
	v_mfma_f32_32x32x16_bf16 v[48:63], v[164:167], v[168:171], v[48:63]
	ds_read_b64_tr_b16 v[160:161], v251 offset:28672
	ds_read_b64_tr_b16 v[162:163], v252 offset:28672
	ds_read_b64_tr_b16 v[168:169], v235 offset:28672
	s_waitcnt lgkmcnt(9)
	v_mfma_f32_32x32x16_bf16 v[64:79], v[2:5], v[10:13], v[64:79]
	ds_read_b64_tr_b16 v[170:171], v255 offset:28672
	ds_read_b64_tr_b16 v[164:165], v253 offset:28672
	ds_read_b64_tr_b16 v[166:167], v200 offset:28672
	v_mfma_f32_32x32x16_bf16 v[48:63], v[6:9], v[10:13], v[48:63]
	s_waitcnt lgkmcnt(6)
	v_mfma_f32_32x32x16_bf16 v[64:79], v[236:239], v[244:247], v[64:79]
	v_mfma_f32_32x32x16_bf16 v[48:63], v[240:243], v[244:247], v[48:63]
	s_waitcnt lgkmcnt(0)
	v_mfma_f32_32x32x16_bf16 v[64:79], v[160:163], v[168:171], v[64:79]
	v_mfma_f32_32x32x16_bf16 v[48:63], v[164:167], v[168:171], v[48:63]
	s_branch .Lret_b0_end
.Lret_b0_b:
	ds_read_b128 v[2:5], v250
	ds_read_b128 v[10:13], v194
	v_xor_b32_e32 v15, 32, v250
	ds_read_b128 v[236:239], v15
	ds_read_b128 v[244:247], v194 offset:32
	v_xor_b32_e32 v15, 64, v250
	ds_read_b128 v[160:163], v15
	s_waitcnt lgkmcnt(3)
	v_mfma_f32_32x32x16_bf16 v[128:143], v[2:5], v[10:13], v[128:143]
	ds_read_b128 v[168:171], v194 offset:64
	v_xor_b32_e32 v15, 0x60, v250
	ds_read_b128 v[2:5], v15
	s_waitcnt lgkmcnt(3)
	v_mfma_f32_32x32x16_bf16 v[128:143], v[236:239], v[244:247], v[128:143]
	ds_read_b128 v[10:13], v194 offset:96
	v_xor_b32_e32 v15, 0x80, v250
	ds_read_b128 v[236:239], v15
	s_waitcnt lgkmcnt(3)
	v_mfma_f32_32x32x16_bf16 v[128:143], v[160:163], v[168:171], v[128:143]
	ds_read_b128 v[244:247], v194 offset:128
	v_xor_b32_e32 v15, 0xa0, v250
	ds_read_b128 v[160:163], v15
	s_waitcnt lgkmcnt(3)
	v_mfma_f32_32x32x16_bf16 v[128:143], v[2:5], v[10:13], v[128:143]
	ds_read_b128 v[168:171], v194 offset:160
	v_xor_b32_e32 v15, 0xc0, v250
	ds_read_b128 v[2:5], v15
	s_waitcnt lgkmcnt(3)
	v_mfma_f32_32x32x16_bf16 v[128:143], v[236:239], v[244:247], v[128:143]
	ds_read_b128 v[10:13], v194 offset:192
	v_xor_b32_e32 v15, 0xe0, v250
	ds_read_b128 v[236:239], v15
	s_waitcnt lgkmcnt(3)
	v_mfma_f32_32x32x16_bf16 v[128:143], v[160:163], v[168:171], v[128:143]
	ds_read_b128 v[244:247], v194 offset:224
	ds_read_b128 v[160:163], v14
	ds_read_b128 v[164:167], v195
	s_waitcnt lgkmcnt(4)
	v_mfma_f32_32x32x16_bf16 v[128:143], v[2:5], v[10:13], v[128:143]
	ds_read_b128 v[168:171], v195 offset:8704
	ds_read_b128 v[2:5], v14 offset:32
	ds_read_b128 v[6:9], v195 offset:32
	s_waitcnt lgkmcnt(5)
	v_mfma_f32_32x32x16_bf16 v[128:143], v[236:239], v[244:247], v[128:143]
	ds_read_b128 v[10:13], v195 offset:8736
	ds_read_b128 v[236:239], v14 offset:64
	ds_read_b128 v[240:243], v195 offset:64
	s_waitcnt lgkmcnt(5)
	v_mfma_f32_32x32x16_bf16 v[96:111], v[160:163], v[164:167], v[96:111]
	ds_read_b128 v[244:247], v195 offset:8768
	v_mfma_f32_32x32x16_bf16 v[80:95], v[160:163], v[168:171], v[80:95]
	ds_read_b128 v[160:163], v14 offset:96
	ds_read_b128 v[164:167], v195 offset:96
	s_waitcnt lgkmcnt(5)
	v_mfma_f32_32x32x16_bf16 v[96:111], v[2:5], v[6:9], v[96:111]
	ds_read_b128 v[168:171], v195 offset:8800
	v_mfma_f32_32x32x16_bf16 v[80:95], v[2:5], v[10:13], v[80:95]
	ds_read_b128 v[2:5], v14 offset:128
	ds_read_b128 v[6:9], v195 offset:128
	s_waitcnt lgkmcnt(5)
	v_mfma_f32_32x32x16_bf16 v[96:111], v[236:239], v[240:243], v[96:111]
	ds_read_b128 v[10:13], v195 offset:8832
	v_mfma_f32_32x32x16_bf16 v[80:95], v[236:239], v[244:247], v[80:95]
	ds_read_b128 v[236:239], v14 offset:160
	ds_read_b128 v[240:243], v195 offset:160
	s_waitcnt lgkmcnt(5)
	v_mfma_f32_32x32x16_bf16 v[96:111], v[160:163], v[164:167], v[96:111]
	ds_read_b128 v[244:247], v195 offset:8864
	v_mfma_f32_32x32x16_bf16 v[80:95], v[160:163], v[168:171], v[80:95]
	ds_read_b128 v[160:163], v14 offset:192
	ds_read_b128 v[164:167], v195 offset:192
	s_waitcnt lgkmcnt(5)
	v_mfma_f32_32x32x16_bf16 v[96:111], v[2:5], v[6:9], v[96:111]
	ds_read_b128 v[168:171], v195 offset:8896
	v_mfma_f32_32x32x16_bf16 v[80:95], v[2:5], v[10:13], v[80:95]
	ds_read_b128 v[2:5], v14 offset:224
	ds_read_b128 v[6:9], v195 offset:224
	s_waitcnt lgkmcnt(5)
	v_mfma_f32_32x32x16_bf16 v[96:111], v[236:239], v[240:243], v[96:111]
	ds_read_b128 v[10:13], v195 offset:8928
	v_mfma_f32_32x32x16_bf16 v[80:95], v[236:239], v[244:247], v[80:95]
	ds_read_b64_tr_b16 v[236:237], v251
	ds_read_b64_tr_b16 v[238:239], v252
	ds_read_b64_tr_b16 v[244:245], v235
	s_waitcnt lgkmcnt(6)
	v_mfma_f32_32x32x16_bf16 v[96:111], v[160:163], v[164:167], v[96:111]
	ds_read_b64_tr_b16 v[246:247], v255
	ds_read_b64_tr_b16 v[240:241], v253
	ds_read_b64_tr_b16 v[242:243], v200
	v_mfma_f32_32x32x16_bf16 v[80:95], v[160:163], v[168:171], v[80:95]
	ds_read_b64_tr_b16 v[160:161], v251 offset:4096
	ds_read_b64_tr_b16 v[162:163], v252 offset:4096
	ds_read_b64_tr_b16 v[168:169], v235 offset:4096
	s_waitcnt lgkmcnt(9)
	v_mfma_f32_32x32x16_bf16 v[96:111], v[2:5], v[6:9], v[96:111]
	ds_read_b64_tr_b16 v[170:171], v255 offset:4096
	ds_read_b64_tr_b16 v[164:165], v253 offset:4096
	ds_read_b64_tr_b16 v[166:167], v200 offset:4096
	v_mfma_f32_32x32x16_bf16 v[80:95], v[2:5], v[10:13], v[80:95]
	ds_read_b64_tr_b16 v[2:3], v251 offset:8192
	ds_read_b64_tr_b16 v[4:5], v252 offset:8192
	ds_read_b64_tr_b16 v[10:11], v235 offset:8192
	s_waitcnt lgkmcnt(9)
	v_mfma_f32_32x32x16_bf16 v[64:79], v[236:239], v[244:247], v[64:79]
	ds_read_b64_tr_b16 v[12:13], v255 offset:8192
	ds_read_b64_tr_b16 v[6:7], v253 offset:8192
	ds_read_b64_tr_b16 v[8:9], v200 offset:8192
	v_mfma_f32_32x32x16_bf16 v[48:63], v[240:243], v[244:247], v[48:63]
	ds_read_b64_tr_b16 v[236:237], v251 offset:12288
	ds_read_b64_tr_b16 v[238:239], v252 offset:12288
	ds_read_b64_tr_b16 v[244:245], v235 offset:12288
	s_waitcnt lgkmcnt(9)
	v_mfma_f32_32x32x16_bf16 v[64:79], v[160:163], v[168:171], v[64:79]
	ds_read_b64_tr_b16 v[246:247], v255 offset:12288
	ds_read_b64_tr_b16 v[240:241], v253 offset:12288
	ds_read_b64_tr_b16 v[242:243], v200 offset:12288
	v_mfma_f32_32x32x16_bf16 v[48:63], v[164:167], v[168:171], v[48:63]
	ds_read_b64_tr_b16 v[160:161], v251 offset:16384
	ds_read_b64_tr_b16 v[162:163], v252 offset:16384
	ds_read_b64_tr_b16 v[168:169], v235 offset:16384
	s_waitcnt lgkmcnt(9)
	v_mfma_f32_32x32x16_bf16 v[64:79], v[2:5], v[10:13], v[64:79]
	ds_read_b64_tr_b16 v[170:171], v255 offset:16384
	ds_read_b64_tr_b16 v[164:165], v253 offset:16384
	ds_read_b64_tr_b16 v[166:167], v200 offset:16384
	v_mfma_f32_32x32x16_bf16 v[48:63], v[6:9], v[10:13], v[48:63]
	ds_read_b64_tr_b16 v[2:3], v251 offset:20480
	ds_read_b64_tr_b16 v[4:5], v252 offset:20480
	ds_read_b64_tr_b16 v[10:11], v235 offset:20480
	s_waitcnt lgkmcnt(9)
	v_mfma_f32_32x32x16_bf16 v[64:79], v[236:239], v[244:247], v[64:79]
	ds_read_b64_tr_b16 v[12:13], v255 offset:20480
	ds_read_b64_tr_b16 v[6:7], v253 offset:20480
	ds_read_b64_tr_b16 v[8:9], v200 offset:20480
	v_mfma_f32_32x32x16_bf16 v[48:63], v[240:243], v[244:247], v[48:63]
	ds_read_b64_tr_b16 v[236:237], v251 offset:24576
	ds_read_b64_tr_b16 v[238:239], v252 offset:24576
	ds_read_b64_tr_b16 v[244:245], v235 offset:24576
	s_waitcnt lgkmcnt(9)
	v_mfma_f32_32x32x16_bf16 v[64:79], v[160:163], v[168:171], v[64:79]
	ds_read_b64_tr_b16 v[246:247], v255 offset:24576
	ds_read_b64_tr_b16 v[240:241], v253 offset:24576
	ds_read_b64_tr_b16 v[242:243], v200 offset:24576
	v_mfma_f32_32x32x16_bf16 v[48:63], v[164:167], v[168:171], v[48:63]
	ds_read_b64_tr_b16 v[160:161], v251 offset:28672
	ds_read_b64_tr_b16 v[162:163], v252 offset:28672
	ds_read_b64_tr_b16 v[168:169], v235 offset:28672
	s_waitcnt lgkmcnt(9)
	v_mfma_f32_32x32x16_bf16 v[64:79], v[2:5], v[10:13], v[64:79]
	ds_read_b64_tr_b16 v[170:171], v255 offset:28672
	ds_read_b64_tr_b16 v[164:165], v253 offset:28672
	ds_read_b64_tr_b16 v[166:167], v200 offset:28672
	v_mfma_f32_32x32x16_bf16 v[48:63], v[6:9], v[10:13], v[48:63]
	s_waitcnt lgkmcnt(6)
	v_mfma_f32_32x32x16_bf16 v[64:79], v[236:239], v[244:247], v[64:79]
	v_mfma_f32_32x32x16_bf16 v[48:63], v[240:243], v[244:247], v[48:63]
	s_waitcnt lgkmcnt(0)
	v_mfma_f32_32x32x16_bf16 v[64:79], v[160:163], v[168:171], v[64:79]
	v_mfma_f32_32x32x16_bf16 v[48:63], v[164:167], v[168:171], v[48:63]
	s_branch .Lret_b0_end
.Lret_b0_c:
	ds_read_b128 v[2:5], v14
	ds_read_b128 v[6:9], v195
	ds_read_b128 v[10:13], v195 offset:8704
	ds_read_b128 v[236:239], v14 offset:32
	ds_read_b128 v[240:243], v195 offset:32
	ds_read_b128 v[244:247], v195 offset:8736
	ds_read_b128 v[160:163], v14 offset:64
	ds_read_b128 v[164:167], v195 offset:64
	s_waitcnt lgkmcnt(5)
	v_mfma_f32_32x32x16_bf16 v[96:111], v[2:5], v[6:9], v[96:111]
	ds_read_b128 v[168:171], v195 offset:8768
	v_mfma_f32_32x32x16_bf16 v[80:95], v[2:5], v[10:13], v[80:95]
	ds_read_b128 v[2:5], v14 offset:96
	ds_read_b128 v[6:9], v195 offset:96
	s_waitcnt lgkmcnt(5)
	v_mfma_f32_32x32x16_bf16 v[96:111], v[236:239], v[240:243], v[96:111]
	ds_read_b128 v[10:13], v195 offset:8800
	v_mfma_f32_32x32x16_bf16 v[80:95], v[236:239], v[244:247], v[80:95]
	ds_read_b128 v[236:239], v14 offset:128
	ds_read_b128 v[240:243], v195 offset:128
	s_waitcnt lgkmcnt(5)
	v_mfma_f32_32x32x16_bf16 v[96:111], v[160:163], v[164:167], v[96:111]
	ds_read_b128 v[244:247], v195 offset:8832
	v_mfma_f32_32x32x16_bf16 v[80:95], v[160:163], v[168:171], v[80:95]
	ds_read_b128 v[160:163], v14 offset:160
	ds_read_b128 v[164:167], v195 offset:160
	s_waitcnt lgkmcnt(5)
	v_mfma_f32_32x32x16_bf16 v[96:111], v[2:5], v[6:9], v[96:111]
	ds_read_b128 v[168:171], v195 offset:8864
	v_mfma_f32_32x32x16_bf16 v[80:95], v[2:5], v[10:13], v[80:95]
	ds_read_b128 v[2:5], v14 offset:192
	ds_read_b128 v[6:9], v195 offset:192
	s_waitcnt lgkmcnt(5)
	v_mfma_f32_32x32x16_bf16 v[96:111], v[236:239], v[240:243], v[96:111]
	ds_read_b128 v[10:13], v195 offset:8896
	v_mfma_f32_32x32x16_bf16 v[80:95], v[236:239], v[244:247], v[80:95]
	ds_read_b128 v[236:239], v14 offset:224
	ds_read_b128 v[240:243], v195 offset:224
	s_waitcnt lgkmcnt(5)
	v_mfma_f32_32x32x16_bf16 v[96:111], v[160:163], v[164:167], v[96:111]
	ds_read_b128 v[244:247], v195 offset:8928
	v_mfma_f32_32x32x16_bf16 v[80:95], v[160:163], v[168:171], v[80:95]
	ds_read_b64_tr_b16 v[160:161], v251
	ds_read_b64_tr_b16 v[162:163], v252
	ds_read_b64_tr_b16 v[168:169], v235
	s_waitcnt lgkmcnt(6)
	v_mfma_f32_32x32x16_bf16 v[96:111], v[2:5], v[6:9], v[96:111]
	ds_read_b64_tr_b16 v[170:171], v255
	ds_read_b64_tr_b16 v[164:165], v253
	ds_read_b64_tr_b16 v[166:167], v200
	v_mfma_f32_32x32x16_bf16 v[80:95], v[2:5], v[10:13], v[80:95]
	ds_read_b64_tr_b16 v[2:3], v251 offset:4096
	ds_read_b64_tr_b16 v[4:5], v252 offset:4096
	ds_read_b64_tr_b16 v[10:11], v235 offset:4096
	s_waitcnt lgkmcnt(9)
	v_mfma_f32_32x32x16_bf16 v[96:111], v[236:239], v[240:243], v[96:111]
	ds_read_b64_tr_b16 v[12:13], v255 offset:4096
	ds_read_b64_tr_b16 v[6:7], v253 offset:4096
	ds_read_b64_tr_b16 v[8:9], v200 offset:4096
	v_mfma_f32_32x32x16_bf16 v[80:95], v[236:239], v[244:247], v[80:95]
	ds_read_b64_tr_b16 v[236:237], v251 offset:8192
	ds_read_b64_tr_b16 v[238:239], v252 offset:8192
	ds_read_b64_tr_b16 v[244:245], v235 offset:8192
	s_waitcnt lgkmcnt(9)
	v_mfma_f32_32x32x16_bf16 v[64:79], v[160:163], v[168:171], v[64:79]
	ds_read_b64_tr_b16 v[246:247], v255 offset:8192
	ds_read_b64_tr_b16 v[240:241], v253 offset:8192
	ds_read_b64_tr_b16 v[242:243], v200 offset:8192
	v_mfma_f32_32x32x16_bf16 v[48:63], v[164:167], v[168:171], v[48:63]
	ds_read_b64_tr_b16 v[160:161], v251 offset:12288
	ds_read_b64_tr_b16 v[162:163], v252 offset:12288
	ds_read_b64_tr_b16 v[168:169], v235 offset:12288
	s_waitcnt lgkmcnt(9)
	v_mfma_f32_32x32x16_bf16 v[64:79], v[2:5], v[10:13], v[64:79]
	ds_read_b64_tr_b16 v[170:171], v255 offset:12288
	ds_read_b64_tr_b16 v[164:165], v253 offset:12288
	ds_read_b64_tr_b16 v[166:167], v200 offset:12288
	v_mfma_f32_32x32x16_bf16 v[48:63], v[6:9], v[10:13], v[48:63]
	ds_read_b64_tr_b16 v[2:3], v251 offset:16384
	ds_read_b64_tr_b16 v[4:5], v252 offset:16384
	ds_read_b64_tr_b16 v[10:11], v235 offset:16384
	s_waitcnt lgkmcnt(9)
	v_mfma_f32_32x32x16_bf16 v[64:79], v[236:239], v[244:247], v[64:79]
	ds_read_b64_tr_b16 v[12:13], v255 offset:16384
	ds_read_b64_tr_b16 v[6:7], v253 offset:16384
	ds_read_b64_tr_b16 v[8:9], v200 offset:16384
	v_mfma_f32_32x32x16_bf16 v[48:63], v[240:243], v[244:247], v[48:63]
	ds_read_b64_tr_b16 v[236:237], v251 offset:20480
	ds_read_b64_tr_b16 v[238:239], v252 offset:20480
	ds_read_b64_tr_b16 v[244:245], v235 offset:20480
	s_waitcnt lgkmcnt(9)
	v_mfma_f32_32x32x16_bf16 v[64:79], v[160:163], v[168:171], v[64:79]
	ds_read_b64_tr_b16 v[246:247], v255 offset:20480
	ds_read_b64_tr_b16 v[240:241], v253 offset:20480
	ds_read_b64_tr_b16 v[242:243], v200 offset:20480
	v_mfma_f32_32x32x16_bf16 v[48:63], v[164:167], v[168:171], v[48:63]
	ds_read_b64_tr_b16 v[160:161], v251 offset:24576
	ds_read_b64_tr_b16 v[162:163], v252 offset:24576
	ds_read_b64_tr_b16 v[168:169], v235 offset:24576
	s_waitcnt lgkmcnt(9)
	v_mfma_f32_32x32x16_bf16 v[64:79], v[2:5], v[10:13], v[64:79]
	ds_read_b64_tr_b16 v[170:171], v255 offset:24576
	ds_read_b64_tr_b16 v[164:165], v253 offset:24576
	ds_read_b64_tr_b16 v[166:167], v200 offset:24576
	v_mfma_f32_32x32x16_bf16 v[48:63], v[6:9], v[10:13], v[48:63]
	ds_read_b64_tr_b16 v[2:3], v251 offset:28672
	ds_read_b64_tr_b16 v[4:5], v252 offset:28672
	ds_read_b64_tr_b16 v[10:11], v235 offset:28672
	s_waitcnt lgkmcnt(9)
	v_mfma_f32_32x32x16_bf16 v[64:79], v[236:239], v[244:247], v[64:79]
	ds_read_b64_tr_b16 v[12:13], v255 offset:28672
	ds_read_b64_tr_b16 v[6:7], v253 offset:28672
	ds_read_b64_tr_b16 v[8:9], v200 offset:28672
	v_mfma_f32_32x32x16_bf16 v[48:63], v[240:243], v[244:247], v[48:63]
	s_waitcnt lgkmcnt(6)
	v_mfma_f32_32x32x16_bf16 v[64:79], v[160:163], v[168:171], v[64:79]
	v_mfma_f32_32x32x16_bf16 v[48:63], v[164:167], v[168:171], v[48:63]
	s_waitcnt lgkmcnt(0)
	v_mfma_f32_32x32x16_bf16 v[64:79], v[2:5], v[10:13], v[64:79]
	v_mfma_f32_32x32x16_bf16 v[48:63], v[6:9], v[10:13], v[48:63]
	s_branch .Lret_b0_end
.Lret_b0_ctx:
	v_mov_b32_e32 v80, 0
	v_mov_b32_e32 v81, 0
	v_mov_b32_e32 v82, 0
	v_mov_b32_e32 v83, 0
	v_mov_b32_e32 v84, 0
	v_mov_b32_e32 v85, 0
	v_mov_b32_e32 v86, 0
	v_mov_b32_e32 v87, 0
	v_mov_b32_e32 v88, 0
	v_mov_b32_e32 v89, 0
	v_mov_b32_e32 v90, 0
	v_mov_b32_e32 v91, 0
	v_mov_b32_e32 v92, 0
	v_mov_b32_e32 v93, 0
	v_mov_b32_e32 v94, 0
	v_mov_b32_e32 v95, 0
	v_mov_b32_e32 v96, 0
	v_mov_b32_e32 v97, 0
	v_mov_b32_e32 v98, 0
	v_mov_b32_e32 v99, 0
	v_mov_b32_e32 v100, 0
	v_mov_b32_e32 v101, 0
	v_mov_b32_e32 v102, 0
	v_mov_b32_e32 v103, 0
	v_mov_b32_e32 v104, 0
	v_mov_b32_e32 v105, 0
	v_mov_b32_e32 v106, 0
	v_mov_b32_e32 v107, 0
	v_mov_b32_e32 v108, 0
	v_mov_b32_e32 v109, 0
	v_mov_b32_e32 v110, 0
	v_mov_b32_e32 v111, 0
	v_mov_b32_e32 v112, 0
	v_mov_b32_e32 v113, 0
	v_mov_b32_e32 v114, 0
	v_mov_b32_e32 v115, 0
	v_mov_b32_e32 v116, 0
	v_mov_b32_e32 v117, 0
	v_mov_b32_e32 v118, 0
	v_mov_b32_e32 v119, 0
	v_mov_b32_e32 v120, 0
	v_mov_b32_e32 v121, 0
	v_mov_b32_e32 v122, 0
	v_mov_b32_e32 v123, 0
	v_mov_b32_e32 v124, 0
	v_mov_b32_e32 v125, 0
	v_mov_b32_e32 v126, 0
	v_mov_b32_e32 v127, 0
	v_mov_b32_e32 v128, 0
	v_mov_b32_e32 v129, 0
	v_mov_b32_e32 v130, 0
	v_mov_b32_e32 v131, 0
	v_mov_b32_e32 v132, 0
	v_mov_b32_e32 v133, 0
	v_mov_b32_e32 v134, 0
	v_mov_b32_e32 v135, 0
	v_mov_b32_e32 v136, 0
	v_mov_b32_e32 v137, 0
	v_mov_b32_e32 v138, 0
	v_mov_b32_e32 v139, 0
	v_mov_b32_e32 v140, 0
	v_mov_b32_e32 v141, 0
	v_mov_b32_e32 v142, 0
	v_mov_b32_e32 v143, 0
	ds_read_b64_tr_b16 v[2:3], v251
	ds_read_b64_tr_b16 v[4:5], v252
	ds_read_b64_tr_b16 v[10:11], v235
	ds_read_b64_tr_b16 v[12:13], v255
	ds_read_b64_tr_b16 v[6:7], v253
	ds_read_b64_tr_b16 v[8:9], v200
	ds_read_b64_tr_b16 v[236:237], v251 offset:4096
	ds_read_b64_tr_b16 v[238:239], v252 offset:4096
	ds_read_b64_tr_b16 v[244:245], v235 offset:4096
	ds_read_b64_tr_b16 v[246:247], v255 offset:4096
	ds_read_b64_tr_b16 v[240:241], v253 offset:4096
	ds_read_b64_tr_b16 v[242:243], v200 offset:4096
	ds_read_b64_tr_b16 v[160:161], v251 offset:8192
	ds_read_b64_tr_b16 v[162:163], v252 offset:8192
	ds_read_b64_tr_b16 v[168:169], v235 offset:8192
	s_waitcnt lgkmcnt(9)
	v_mfma_f32_32x32x16_bf16 v[64:79], v[2:5], v[10:13], v[64:79]
	ds_read_b64_tr_b16 v[170:171], v255 offset:8192
	ds_read_b64_tr_b16 v[164:165], v253 offset:8192
	ds_read_b64_tr_b16 v[166:167], v200 offset:8192
	v_mfma_f32_32x32x16_bf16 v[48:63], v[6:9], v[10:13], v[48:63]
	ds_read_b64_tr_b16 v[2:3], v251 offset:12288
	ds_read_b64_tr_b16 v[4:5], v252 offset:12288
	ds_read_b64_tr_b16 v[10:11], v235 offset:12288
	s_waitcnt lgkmcnt(9)
	v_mfma_f32_32x32x16_bf16 v[64:79], v[236:239], v[244:247], v[64:79]
	ds_read_b64_tr_b16 v[12:13], v255 offset:12288
	ds_read_b64_tr_b16 v[6:7], v253 offset:12288
	ds_read_b64_tr_b16 v[8:9], v200 offset:12288
	v_mfma_f32_32x32x16_bf16 v[48:63], v[240:243], v[244:247], v[48:63]
	ds_read_b64_tr_b16 v[236:237], v251 offset:16384
	ds_read_b64_tr_b16 v[238:239], v252 offset:16384
	ds_read_b64_tr_b16 v[244:245], v235 offset:16384
	s_waitcnt lgkmcnt(9)
	v_mfma_f32_32x32x16_bf16 v[64:79], v[160:163], v[168:171], v[64:79]
	ds_read_b64_tr_b16 v[246:247], v255 offset:16384
	ds_read_b64_tr_b16 v[240:241], v253 offset:16384
	ds_read_b64_tr_b16 v[242:243], v200 offset:16384
	v_mfma_f32_32x32x16_bf16 v[48:63], v[164:167], v[168:171], v[48:63]
	ds_read_b64_tr_b16 v[160:161], v251 offset:20480
	ds_read_b64_tr_b16 v[162:163], v252 offset:20480
	ds_read_b64_tr_b16 v[168:169], v235 offset:20480
	s_waitcnt lgkmcnt(9)
	v_mfma_f32_32x32x16_bf16 v[64:79], v[2:5], v[10:13], v[64:79]
	ds_read_b64_tr_b16 v[170:171], v255 offset:20480
	ds_read_b64_tr_b16 v[164:165], v253 offset:20480
	ds_read_b64_tr_b16 v[166:167], v200 offset:20480
	v_mfma_f32_32x32x16_bf16 v[48:63], v[6:9], v[10:13], v[48:63]
	ds_read_b64_tr_b16 v[2:3], v251 offset:24576
	ds_read_b64_tr_b16 v[4:5], v252 offset:24576
	ds_read_b64_tr_b16 v[10:11], v235 offset:24576
	s_waitcnt lgkmcnt(9)
	v_mfma_f32_32x32x16_bf16 v[64:79], v[236:239], v[244:247], v[64:79]
	ds_read_b64_tr_b16 v[12:13], v255 offset:24576
	ds_read_b64_tr_b16 v[6:7], v253 offset:24576
	ds_read_b64_tr_b16 v[8:9], v200 offset:24576
	v_mfma_f32_32x32x16_bf16 v[48:63], v[240:243], v[244:247], v[48:63]
	ds_read_b64_tr_b16 v[236:237], v251 offset:28672
	ds_read_b64_tr_b16 v[238:239], v252 offset:28672
	ds_read_b64_tr_b16 v[244:245], v235 offset:28672
	s_waitcnt lgkmcnt(9)
	v_mfma_f32_32x32x16_bf16 v[64:79], v[160:163], v[168:171], v[64:79]
	ds_read_b64_tr_b16 v[246:247], v255 offset:28672
	ds_read_b64_tr_b16 v[240:241], v253 offset:28672
	ds_read_b64_tr_b16 v[242:243], v200 offset:28672
	v_mfma_f32_32x32x16_bf16 v[48:63], v[164:167], v[168:171], v[48:63]
	s_waitcnt lgkmcnt(6)
	v_mfma_f32_32x32x16_bf16 v[64:79], v[2:5], v[10:13], v[64:79]
	v_mfma_f32_32x32x16_bf16 v[48:63], v[6:9], v[10:13], v[48:63]
	s_waitcnt lgkmcnt(0)
	v_mfma_f32_32x32x16_bf16 v[64:79], v[236:239], v[244:247], v[64:79]
	v_mfma_f32_32x32x16_bf16 v[48:63], v[240:243], v[244:247], v[48:63]

.LBB0_929:
	s_and_b64 vcc, exec, s[16:17]
	s_waitcnt vmcnt(1)
	ds_write_b128 v249, v[180:183] offset:51200
	s_waitcnt vmcnt(0)
	ds_write_b128 v249, v[176:179] offset:59392
	s_cbranch_vccnz .LBB0_931

.LBB0_941:
	s_and_b64 vcc, exec, s[16:17]
	s_waitcnt lgkmcnt(0)
	s_barrier
	s_cbranch_vccnz .Lret_d1_ctx
	v_add_u32_e32 v14, 0x19800, v212
	s_and_b64 vcc, exec, s[2:3]
	s_cbranch_vccz .Lret_d1_c
	s_and_b64 vcc, exec, s[4:5]
	s_cbranch_vccz .Lret_d1_b
	ds_read_b128 v[2:5], v250
	ds_read_b128 v[6:9], v250 offset:8192
	ds_read_b128 v[10:13], v194
	v_xor_b32_e32 v15, 32, v250
	ds_read_b128 v[236:239], v15
	ds_read_b128 v[240:243], v15 offset:8192
	ds_read_b128 v[244:247], v194 offset:32
	v_xor_b32_e32 v15, 64, v250
	ds_read_b128 v[160:163], v15
	ds_read_b128 v[164:167], v15 offset:8192
	s_waitcnt lgkmcnt(5)
	v_mfma_f32_32x32x16_bf16 v[128:143], v[2:5], v[10:13], v[128:143]
	ds_read_b128 v[168:171], v194 offset:64
	v_mfma_f32_32x32x16_bf16 v[112:127], v[6:9], v[10:13], v[112:127]
	v_xor_b32_e32 v15, 0x60, v250
	ds_read_b128 v[2:5], v15
	ds_read_b128 v[6:9], v15 offset:8192
	s_waitcnt lgkmcnt(5)
	v_mfma_f32_32x32x16_bf16 v[128:143], v[236:239], v[244:247], v[128:143]
	ds_read_b128 v[10:13], v194 offset:96
	v_mfma_f32_32x32x16_bf16 v[112:127], v[240:243], v[244:247], v[112:127]
	v_xor_b32_e32 v15, 0x80, v250
	ds_read_b128 v[236:239], v15
	ds_read_b128 v[240:243], v15 offset:8192
	s_waitcnt lgkmcnt(5)
	v_mfma_f32_32x32x16_bf16 v[128:143], v[160:163], v[168:171], v[128:143]
	ds_read_b128 v[244:247], v194 offset:128
	v_mfma_f32_32x32x16_bf16 v[112:127], v[164:167], v[168:171], v[112:127]
	v_xor_b32_e32 v15, 0xa0, v250
	ds_read_b128 v[160:163], v15
	ds_read_b128 v[164:167], v15 offset:8192
	s_waitcnt lgkmcnt(5)
	v_mfma_f32_32x32x16_bf16 v[128:143], v[2:5], v[10:13], v[128:143]
	ds_read_b128 v[168:171], v194 offset:160
	v_mfma_f32_32x32x16_bf16 v[112:127], v[6:9], v[10:13], v[112:127]
	v_xor_b32_e32 v15, 0xc0, v250
	ds_read_b128 v[2:5], v15
	ds_read_b128 v[6:9], v15 offset:8192
	s_waitcnt lgkmcnt(5)
	v_mfma_f32_32x32x16_bf16 v[128:143], v[236:239], v[244:247], v[128:143]
	ds_read_b128 v[10:13], v194 offset:192
	v_mfma_f32_32x32x16_bf16 v[112:127], v[240:243], v[244:247], v[112:127]
	v_xor_b32_e32 v15, 0xe0, v250
	ds_read_b128 v[236:239], v15
	ds_read_b128 v[240:243], v15 offset:8192
	s_waitcnt lgkmcnt(5)
	v_mfma_f32_32x32x16_bf16 v[128:143], v[160:163], v[168:171], v[128:143]
	ds_read_b128 v[244:247], v194 offset:224
	v_mfma_f32_32x32x16_bf16 v[112:127], v[164:167], v[168:171], v[112:127]
	ds_read_b128 v[160:163], v14
	ds_read_b128 v[164:167], v195
	s_waitcnt lgkmcnt(5)
	v_mfma_f32_32x32x16_bf16 v[128:143], v[2:5], v[10:13], v[128:143]
	ds_read_b128 v[168:171], v195 offset:8704
	v_mfma_f32_32x32x16_bf16 v[112:127], v[6:9], v[10:13], v[112:127]
	ds_read_b128 v[2:5], v14 offset:32
	ds_read_b128 v[6:9], v195 offset:32
	s_waitcnt lgkmcnt(5)
	v_mfma_f32_32x32x16_bf16 v[128:143], v[236:239], v[244:247], v[128:143]
	ds_read_b128 v[10:13], v195 offset:8736
	v_mfma_f32_32x32x16_bf16 v[112:127], v[240:243], v[244:247], v[112:127]
	ds_read_b128 v[236:239], v14 offset:64
	ds_read_b128 v[240:243], v195 offset:64
	s_waitcnt lgkmcnt(5)
	v_mfma_f32_32x32x16_bf16 v[96:111], v[160:163], v[164:167], v[96:111]
	ds_read_b128 v[244:247], v195 offset:8768
	v_mfma_f32_32x32x16_bf16 v[80:95], v[160:163], v[168:171], v[80:95]
	ds_read_b128 v[160:163], v14 offset:96
	ds_read_b128 v[164:167], v195 offset:96
	s_waitcnt lgkmcnt(5)
	v_mfma_f32_32x32x16_bf16 v[96:111], v[2:5], v[6:9], v[96:111]
	ds_read_b128 v[168:171], v195 offset:8800
	v_mfma_f32_32x32x16_bf16 v[80:95], v[2:5], v[10:13], v[80:95]
	ds_read_b128 v[2:5], v14 offset:128
	ds_read_b128 v[6:9], v195 offset:128
	s_waitcnt lgkmcnt(5)
	v_mfma_f32_32x32x16_bf16 v[96:111], v[236:239], v[240:243], v[96:111]
	ds_read_b128 v[10:13], v195 offset:8832
	v_mfma_f32_32x32x16_bf16 v[80:95], v[236:239], v[244:247], v[80:95]
	ds_read_b128 v[236:239], v14 offset:160
	ds_read_b128 v[240:243], v195 offset:160
	s_waitcnt lgkmcnt(5)
	v_mfma_f32_32x32x16_bf16 v[96:111], v[160:163], v[164:167], v[96:111]
	ds_read_b128 v[244:247], v195 offset:8864
	v_mfma_f32_32x32x16_bf16 v[80:95], v[160:163], v[168:171], v[80:95]
	ds_read_b128 v[160:163], v14 offset:192
	ds_read_b128 v[164:167], v195 offset:192
	s_waitcnt lgkmcnt(5)
	v_mfma_f32_32x32x16_bf16 v[96:111], v[2:5], v[6:9], v[96:111]
	ds_read_b128 v[168:171], v195 offset:8896
	v_mfma_f32_32x32x16_bf16 v[80:95], v[2:5], v[10:13], v[80:95]
	ds_read_b128 v[2:5], v14 offset:224
	ds_read_b128 v[6:9], v195 offset:224
	s_waitcnt lgkmcnt(5)
	v_mfma_f32_32x32x16_bf16 v[96:111], v[236:239], v[240:243], v[96:111]
	ds_read_b128 v[10:13], v195 offset:8928
	v_mfma_f32_32x32x16_bf16 v[80:95], v[236:239], v[244:247], v[80:95]
	ds_read_b64_tr_b16 v[236:237], v251
	ds_read_b64_tr_b16 v[238:239], v252
	ds_read_b64_tr_b16 v[244:245], v235
	s_waitcnt lgkmcnt(6)
	v_mfma_f32_32x32x16_bf16 v[96:111], v[160:163], v[164:167], v[96:111]
	ds_read_b64_tr_b16 v[246:247], v255
	ds_read_b64_tr_b16 v[240:241], v253
	ds_read_b64_tr_b16 v[242:243], v200
	v_mfma_f32_32x32x16_bf16 v[80:95], v[160:163], v[168:171], v[80:95]
	ds_read_b64_tr_b16 v[160:161], v251 offset:4096
	ds_read_b64_tr_b16 v[162:163], v252 offset:4096
	ds_read_b64_tr_b16 v[168:169], v235 offset:4096
	s_waitcnt lgkmcnt(9)
	v_mfma_f32_32x32x16_bf16 v[96:111], v[2:5], v[6:9], v[96:111]
	ds_read_b64_tr_b16 v[170:171], v255 offset:4096
	ds_read_b64_tr_b16 v[164:165], v253 offset:4096
	ds_read_b64_tr_b16 v[166:167], v200 offset:4096
	v_mfma_f32_32x32x16_bf16 v[80:95], v[2:5], v[10:13], v[80:95]
	ds_read_b64_tr_b16 v[2:3], v251 offset:8192
	ds_read_b64_tr_b16 v[4:5], v252 offset:8192
	ds_read_b64_tr_b16 v[10:11], v235 offset:8192
	s_waitcnt lgkmcnt(9)
	v_mfma_f32_32x32x16_bf16 v[32:47], v[236:239], v[244:247], v[32:47]
	ds_read_b64_tr_b16 v[12:13], v255 offset:8192
	ds_read_b64_tr_b16 v[6:7], v253 offset:8192
	ds_read_b64_tr_b16 v[8:9], v200 offset:8192
	v_mfma_f32_32x32x16_bf16 v[16:31], v[240:243], v[244:247], v[16:31]
	ds_read_b64_tr_b16 v[236:237], v251 offset:12288
	ds_read_b64_tr_b16 v[238:239], v252 offset:12288
	ds_read_b64_tr_b16 v[244:245], v235 offset:12288
	s_waitcnt lgkmcnt(9)
	v_mfma_f32_32x32x16_bf16 v[32:47], v[160:163], v[168:171], v[32:47]
	ds_read_b64_tr_b16 v[246:247], v255 offset:12288
	ds_read_b64_tr_b16 v[240:241], v253 offset:12288
	ds_read_b64_tr_b16 v[242:243], v200 offset:12288
	v_mfma_f32_32x32x16_bf16 v[16:31], v[164:167], v[168:171], v[16:31]
	ds_read_b64_tr_b16 v[160:161], v251 offset:16384
	ds_read_b64_tr_b16 v[162:163], v252 offset:16384
	ds_read_b64_tr_b16 v[168:169], v235 offset:16384
	s_waitcnt lgkmcnt(9)
	v_mfma_f32_32x32x16_bf16 v[32:47], v[2:5], v[10:13], v[32:47]
	ds_read_b64_tr_b16 v[170:171], v255 offset:16384
	ds_read_b64_tr_b16 v[164:165], v253 offset:16384
	ds_read_b64_tr_b16 v[166:167], v200 offset:16384
	v_mfma_f32_32x32x16_bf16 v[16:31], v[6:9], v[10:13], v[16:31]
	ds_read_b64_tr_b16 v[2:3], v251 offset:20480
	ds_read_b64_tr_b16 v[4:5], v252 offset:20480
	ds_read_b64_tr_b16 v[10:11], v235 offset:20480
	s_waitcnt lgkmcnt(9)
	v_mfma_f32_32x32x16_bf16 v[32:47], v[236:239], v[244:247], v[32:47]
	ds_read_b64_tr_b16 v[12:13], v255 offset:20480
	ds_read_b64_tr_b16 v[6:7], v253 offset:20480
	ds_read_b64_tr_b16 v[8:9], v200 offset:20480
	v_mfma_f32_32x32x16_bf16 v[16:31], v[240:243], v[244:247], v[16:31]
	ds_read_b64_tr_b16 v[236:237], v251 offset:24576
	ds_read_b64_tr_b16 v[238:239], v252 offset:24576
	ds_read_b64_tr_b16 v[244:245], v235 offset:24576
	s_waitcnt lgkmcnt(9)
	v_mfma_f32_32x32x16_bf16 v[32:47], v[160:163], v[168:171], v[32:47]
	ds_read_b64_tr_b16 v[246:247], v255 offset:24576
	ds_read_b64_tr_b16 v[240:241], v253 offset:24576
	ds_read_b64_tr_b16 v[242:243], v200 offset:24576
	v_mfma_f32_32x32x16_bf16 v[16:31], v[164:167], v[168:171], v[16:31]
	ds_read_b64_tr_b16 v[160:161], v251 offset:28672
	ds_read_b64_tr_b16 v[162:163], v252 offset:28672
	ds_read_b64_tr_b16 v[168:169], v235 offset:28672
	s_waitcnt lgkmcnt(9)
	v_mfma_f32_32x32x16_bf16 v[32:47], v[2:5], v[10:13], v[32:47]
	ds_read_b64_tr_b16 v[170:171], v255 offset:28672
	ds_read_b64_tr_b16 v[164:165], v253 offset:28672
	ds_read_b64_tr_b16 v[166:167], v200 offset:28672
	v_mfma_f32_32x32x16_bf16 v[16:31], v[6:9], v[10:13], v[16:31]
	s_waitcnt lgkmcnt(6)
	v_mfma_f32_32x32x16_bf16 v[32:47], v[236:239], v[244:247], v[32:47]
	v_mfma_f32_32x32x16_bf16 v[16:31], v[240:243], v[244:247], v[16:31]
	s_waitcnt lgkmcnt(0)
	v_mfma_f32_32x32x16_bf16 v[32:47], v[160:163], v[168:171], v[32:47]
	v_mfma_f32_32x32x16_bf16 v[16:31], v[164:167], v[168:171], v[16:31]
	s_branch .Lret_d1_end
.Lret_d1_b:
	ds_read_b128 v[2:5], v250
	ds_read_b128 v[10:13], v194
	v_xor_b32_e32 v15, 32, v250
	ds_read_b128 v[236:239], v15
	ds_read_b128 v[244:247], v194 offset:32
	v_xor_b32_e32 v15, 64, v250
	ds_read_b128 v[160:163], v15
	s_waitcnt lgkmcnt(3)
	v_mfma_f32_32x32x16_bf16 v[128:143], v[2:5], v[10:13], v[128:143]
	ds_read_b128 v[168:171], v194 offset:64
	v_xor_b32_e32 v15, 0x60, v250
	ds_read_b128 v[2:5], v15
	s_waitcnt lgkmcnt(3)
	v_mfma_f32_32x32x16_bf16 v[128:143], v[236:239], v[244:247], v[128:143]
	ds_read_b128 v[10:13], v194 offset:96
	v_xor_b32_e32 v15, 0x80, v250
	ds_read_b128 v[236:239], v15
	s_waitcnt lgkmcnt(3)
	v_mfma_f32_32x32x16_bf16 v[128:143], v[160:163], v[168:171], v[128:143]
	ds_read_b128 v[244:247], v194 offset:128
	v_xor_b32_e32 v15, 0xa0, v250
	ds_read_b128 v[160:163], v15
	s_waitcnt lgkmcnt(3)
	v_mfma_f32_32x32x16_bf16 v[128:143], v[2:5], v[10:13], v[128:143]
	ds_read_b128 v[168:171], v194 offset:160
	v_xor_b32_e32 v15, 0xc0, v250
	ds_read_b128 v[2:5], v15
	s_waitcnt lgkmcnt(3)
	v_mfma_f32_32x32x16_bf16 v[128:143], v[236:239], v[244:247], v[128:143]
	ds_read_b128 v[10:13], v194 offset:192
	v_xor_b32_e32 v15, 0xe0, v250
	ds_read_b128 v[236:239], v15
	s_waitcnt lgkmcnt(3)
	v_mfma_f32_32x32x16_bf16 v[128:143], v[160:163], v[168:171], v[128:143]
	ds_read_b128 v[244:247], v194 offset:224
	ds_read_b128 v[160:163], v14
	ds_read_b128 v[164:167], v195
	s_waitcnt lgkmcnt(4)
	v_mfma_f32_32x32x16_bf16 v[128:143], v[2:5], v[10:13], v[128:143]
	ds_read_b128 v[168:171], v195 offset:8704
	ds_read_b128 v[2:5], v14 offset:32
	ds_read_b128 v[6:9], v195 offset:32
	s_waitcnt lgkmcnt(5)
	v_mfma_f32_32x32x16_bf16 v[128:143], v[236:239], v[244:247], v[128:143]
	ds_read_b128 v[10:13], v195 offset:8736
	ds_read_b128 v[236:239], v14 offset:64
	ds_read_b128 v[240:243], v195 offset:64
	s_waitcnt lgkmcnt(5)
	v_mfma_f32_32x32x16_bf16 v[96:111], v[160:163], v[164:167], v[96:111]
	ds_read_b128 v[244:247], v195 offset:8768
	v_mfma_f32_32x32x16_bf16 v[80:95], v[160:163], v[168:171], v[80:95]
	ds_read_b128 v[160:163], v14 offset:96
	ds_read_b128 v[164:167], v195 offset:96
	s_waitcnt lgkmcnt(5)
	v_mfma_f32_32x32x16_bf16 v[96:111], v[2:5], v[6:9], v[96:111]
	ds_read_b128 v[168:171], v195 offset:8800
	v_mfma_f32_32x32x16_bf16 v[80:95], v[2:5], v[10:13], v[80:95]
	ds_read_b128 v[2:5], v14 offset:128
	ds_read_b128 v[6:9], v195 offset:128
	s_waitcnt lgkmcnt(5)
	v_mfma_f32_32x32x16_bf16 v[96:111], v[236:239], v[240:243], v[96:111]
	ds_read_b128 v[10:13], v195 offset:8832
	v_mfma_f32_32x32x16_bf16 v[80:95], v[236:239], v[244:247], v[80:95]
	ds_read_b128 v[236:239], v14 offset:160
	ds_read_b128 v[240:243], v195 offset:160
	s_waitcnt lgkmcnt(5)
	v_mfma_f32_32x32x16_bf16 v[96:111], v[160:163], v[164:167], v[96:111]
	ds_read_b128 v[244:247], v195 offset:8864
	v_mfma_f32_32x32x16_bf16 v[80:95], v[160:163], v[168:171], v[80:95]
	ds_read_b128 v[160:163], v14 offset:192
	ds_read_b128 v[164:167], v195 offset:192
	s_waitcnt lgkmcnt(5)
	v_mfma_f32_32x32x16_bf16 v[96:111], v[2:5], v[6:9], v[96:111]
	ds_read_b128 v[168:171], v195 offset:8896
	v_mfma_f32_32x32x16_bf16 v[80:95], v[2:5], v[10:13], v[80:95]
	ds_read_b128 v[2:5], v14 offset:224
	ds_read_b128 v[6:9], v195 offset:224
	s_waitcnt lgkmcnt(5)
	v_mfma_f32_32x32x16_bf16 v[96:111], v[236:239], v[240:243], v[96:111]
	ds_read_b128 v[10:13], v195 offset:8928
	v_mfma_f32_32x32x16_bf16 v[80:95], v[236:239], v[244:247], v[80:95]
	ds_read_b64_tr_b16 v[236:237], v251
	ds_read_b64_tr_b16 v[238:239], v252
	ds_read_b64_tr_b16 v[244:245], v235
	s_waitcnt lgkmcnt(6)
	v_mfma_f32_32x32x16_bf16 v[96:111], v[160:163], v[164:167], v[96:111]
	ds_read_b64_tr_b16 v[246:247], v255
	ds_read_b64_tr_b16 v[240:241], v253
	ds_read_b64_tr_b16 v[242:243], v200
	v_mfma_f32_32x32x16_bf16 v[80:95], v[160:163], v[168:171], v[80:95]
	ds_read_b64_tr_b16 v[160:161], v251 offset:4096
	ds_read_b64_tr_b16 v[162:163], v252 offset:4096
	ds_read_b64_tr_b16 v[168:169], v235 offset:4096
	s_waitcnt lgkmcnt(9)
	v_mfma_f32_32x32x16_bf16 v[96:111], v[2:5], v[6:9], v[96:111]
	ds_read_b64_tr_b16 v[170:171], v255 offset:4096
	ds_read_b64_tr_b16 v[164:165], v253 offset:4096
	ds_read_b64_tr_b16 v[166:167], v200 offset:4096
	v_mfma_f32_32x32x16_bf16 v[80:95], v[2:5], v[10:13], v[80:95]
	ds_read_b64_tr_b16 v[2:3], v251 offset:8192
	ds_read_b64_tr_b16 v[4:5], v252 offset:8192
	ds_read_b64_tr_b16 v[10:11], v235 offset:8192
	s_waitcnt lgkmcnt(9)
	v_mfma_f32_32x32x16_bf16 v[32:47], v[236:239], v[244:247], v[32:47]
	ds_read_b64_tr_b16 v[12:13], v255 offset:8192
	ds_read_b64_tr_b16 v[6:7], v253 offset:8192
	ds_read_b64_tr_b16 v[8:9], v200 offset:8192
	v_mfma_f32_32x32x16_bf16 v[16:31], v[240:243], v[244:247], v[16:31]
	ds_read_b64_tr_b16 v[236:237], v251 offset:12288
	ds_read_b64_tr_b16 v[238:239], v252 offset:12288
	ds_read_b64_tr_b16 v[244:245], v235 offset:12288
	s_waitcnt lgkmcnt(9)
	v_mfma_f32_32x32x16_bf16 v[32:47], v[160:163], v[168:171], v[32:47]
	ds_read_b64_tr_b16 v[246:247], v255 offset:12288
	ds_read_b64_tr_b16 v[240:241], v253 offset:12288
	ds_read_b64_tr_b16 v[242:243], v200 offset:12288
	v_mfma_f32_32x32x16_bf16 v[16:31], v[164:167], v[168:171], v[16:31]
	ds_read_b64_tr_b16 v[160:161], v251 offset:16384
	ds_read_b64_tr_b16 v[162:163], v252 offset:16384
	ds_read_b64_tr_b16 v[168:169], v235 offset:16384
	s_waitcnt lgkmcnt(9)
	v_mfma_f32_32x32x16_bf16 v[32:47], v[2:5], v[10:13], v[32:47]
	ds_read_b64_tr_b16 v[170:171], v255 offset:16384
	ds_read_b64_tr_b16 v[164:165], v253 offset:16384
	ds_read_b64_tr_b16 v[166:167], v200 offset:16384
	v_mfma_f32_32x32x16_bf16 v[16:31], v[6:9], v[10:13], v[16:31]
	ds_read_b64_tr_b16 v[2:3], v251 offset:20480
	ds_read_b64_tr_b16 v[4:5], v252 offset:20480
	ds_read_b64_tr_b16 v[10:11], v235 offset:20480
	s_waitcnt lgkmcnt(9)
	v_mfma_f32_32x32x16_bf16 v[32:47], v[236:239], v[244:247], v[32:47]
	ds_read_b64_tr_b16 v[12:13], v255 offset:20480
	ds_read_b64_tr_b16 v[6:7], v253 offset:20480
	ds_read_b64_tr_b16 v[8:9], v200 offset:20480
	v_mfma_f32_32x32x16_bf16 v[16:31], v[240:243], v[244:247], v[16:31]
	ds_read_b64_tr_b16 v[236:237], v251 offset:24576
	ds_read_b64_tr_b16 v[238:239], v252 offset:24576
	ds_read_b64_tr_b16 v[244:245], v235 offset:24576
	s_waitcnt lgkmcnt(9)
	v_mfma_f32_32x32x16_bf16 v[32:47], v[160:163], v[168:171], v[32:47]
	ds_read_b64_tr_b16 v[246:247], v255 offset:24576
	ds_read_b64_tr_b16 v[240:241], v253 offset:24576
	ds_read_b64_tr_b16 v[242:243], v200 offset:24576
	v_mfma_f32_32x32x16_bf16 v[16:31], v[164:167], v[168:171], v[16:31]
	ds_read_b64_tr_b16 v[160:161], v251 offset:28672
	ds_read_b64_tr_b16 v[162:163], v252 offset:28672
	ds_read_b64_tr_b16 v[168:169], v235 offset:28672
	s_waitcnt lgkmcnt(9)
	v_mfma_f32_32x32x16_bf16 v[32:47], v[2:5], v[10:13], v[32:47]
	ds_read_b64_tr_b16 v[170:171], v255 offset:28672
	ds_read_b64_tr_b16 v[164:165], v253 offset:28672
	ds_read_b64_tr_b16 v[166:167], v200 offset:28672
	v_mfma_f32_32x32x16_bf16 v[16:31], v[6:9], v[10:13], v[16:31]
	s_waitcnt lgkmcnt(6)
	v_mfma_f32_32x32x16_bf16 v[32:47], v[236:239], v[244:247], v[32:47]
	v_mfma_f32_32x32x16_bf16 v[16:31], v[240:243], v[244:247], v[16:31]
	s_waitcnt lgkmcnt(0)
	v_mfma_f32_32x32x16_bf16 v[32:47], v[160:163], v[168:171], v[32:47]
	v_mfma_f32_32x32x16_bf16 v[16:31], v[164:167], v[168:171], v[16:31]
	s_branch .Lret_d1_end
.Lret_d1_c:
	ds_read_b128 v[2:5], v14
	ds_read_b128 v[6:9], v195
	ds_read_b128 v[10:13], v195 offset:8704
	ds_read_b128 v[236:239], v14 offset:32
	ds_read_b128 v[240:243], v195 offset:32
	ds_read_b128 v[244:247], v195 offset:8736
	ds_read_b128 v[160:163], v14 offset:64
	ds_read_b128 v[164:167], v195 offset:64
	s_waitcnt lgkmcnt(5)
	v_mfma_f32_32x32x16_bf16 v[96:111], v[2:5], v[6:9], v[96:111]
	ds_read_b128 v[168:171], v195 offset:8768
	v_mfma_f32_32x32x16_bf16 v[80:95], v[2:5], v[10:13], v[80:95]
	ds_read_b128 v[2:5], v14 offset:96
	ds_read_b128 v[6:9], v195 offset:96
	s_waitcnt lgkmcnt(5)
	v_mfma_f32_32x32x16_bf16 v[96:111], v[236:239], v[240:243], v[96:111]
	ds_read_b128 v[10:13], v195 offset:8800
	v_mfma_f32_32x32x16_bf16 v[80:95], v[236:239], v[244:247], v[80:95]
	ds_read_b128 v[236:239], v14 offset:128
	ds_read_b128 v[240:243], v195 offset:128
	s_waitcnt lgkmcnt(5)
	v_mfma_f32_32x32x16_bf16 v[96:111], v[160:163], v[164:167], v[96:111]
	ds_read_b128 v[244:247], v195 offset:8832
	v_mfma_f32_32x32x16_bf16 v[80:95], v[160:163], v[168:171], v[80:95]
	ds_read_b128 v[160:163], v14 offset:160
	ds_read_b128 v[164:167], v195 offset:160
	s_waitcnt lgkmcnt(5)
	v_mfma_f32_32x32x16_bf16 v[96:111], v[2:5], v[6:9], v[96:111]
	ds_read_b128 v[168:171], v195 offset:8864
	v_mfma_f32_32x32x16_bf16 v[80:95], v[2:5], v[10:13], v[80:95]
	ds_read_b128 v[2:5], v14 offset:192
	ds_read_b128 v[6:9], v195 offset:192
	s_waitcnt lgkmcnt(5)
	v_mfma_f32_32x32x16_bf16 v[96:111], v[236:239], v[240:243], v[96:111]
	ds_read_b128 v[10:13], v195 offset:8896
	v_mfma_f32_32x32x16_bf16 v[80:95], v[236:239], v[244:247], v[80:95]
	ds_read_b128 v[236:239], v14 offset:224
	ds_read_b128 v[240:243], v195 offset:224
	s_waitcnt lgkmcnt(5)
	v_mfma_f32_32x32x16_bf16 v[96:111], v[160:163], v[164:167], v[96:111]
	ds_read_b128 v[244:247], v195 offset:8928
	v_mfma_f32_32x32x16_bf16 v[80:95], v[160:163], v[168:171], v[80:95]
	ds_read_b64_tr_b16 v[160:161], v251
	ds_read_b64_tr_b16 v[162:163], v252
	ds_read_b64_tr_b16 v[168:169], v235
	s_waitcnt lgkmcnt(6)
	v_mfma_f32_32x32x16_bf16 v[96:111], v[2:5], v[6:9], v[96:111]
	ds_read_b64_tr_b16 v[170:171], v255
	ds_read_b64_tr_b16 v[164:165], v253
	ds_read_b64_tr_b16 v[166:167], v200
	v_mfma_f32_32x32x16_bf16 v[80:95], v[2:5], v[10:13], v[80:95]
	ds_read_b64_tr_b16 v[2:3], v251 offset:4096
	ds_read_b64_tr_b16 v[4:5], v252 offset:4096
	ds_read_b64_tr_b16 v[10:11], v235 offset:4096
	s_waitcnt lgkmcnt(9)
	v_mfma_f32_32x32x16_bf16 v[96:111], v[236:239], v[240:243], v[96:111]
	ds_read_b64_tr_b16 v[12:13], v255 offset:4096
	ds_read_b64_tr_b16 v[6:7], v253 offset:4096
	ds_read_b64_tr_b16 v[8:9], v200 offset:4096
	v_mfma_f32_32x32x16_bf16 v[80:95], v[236:239], v[244:247], v[80:95]
	ds_read_b64_tr_b16 v[236:237], v251 offset:8192
	ds_read_b64_tr_b16 v[238:239], v252 offset:8192
	ds_read_b64_tr_b16 v[244:245], v235 offset:8192
	s_waitcnt lgkmcnt(9)
	v_mfma_f32_32x32x16_bf16 v[32:47], v[160:163], v[168:171], v[32:47]
	ds_read_b64_tr_b16 v[246:247], v255 offset:8192
	ds_read_b64_tr_b16 v[240:241], v253 offset:8192
	ds_read_b64_tr_b16 v[242:243], v200 offset:8192
	v_mfma_f32_32x32x16_bf16 v[16:31], v[164:167], v[168:171], v[16:31]
	ds_read_b64_tr_b16 v[160:161], v251 offset:12288
	ds_read_b64_tr_b16 v[162:163], v252 offset:12288
	ds_read_b64_tr_b16 v[168:169], v235 offset:12288
	s_waitcnt lgkmcnt(9)
	v_mfma_f32_32x32x16_bf16 v[32:47], v[2:5], v[10:13], v[32:47]
	ds_read_b64_tr_b16 v[170:171], v255 offset:12288
	ds_read_b64_tr_b16 v[164:165], v253 offset:12288
	ds_read_b64_tr_b16 v[166:167], v200 offset:12288
	v_mfma_f32_32x32x16_bf16 v[16:31], v[6:9], v[10:13], v[16:31]
	ds_read_b64_tr_b16 v[2:3], v251 offset:16384
	ds_read_b64_tr_b16 v[4:5], v252 offset:16384
	ds_read_b64_tr_b16 v[10:11], v235 offset:16384
	s_waitcnt lgkmcnt(9)
	v_mfma_f32_32x32x16_bf16 v[32:47], v[236:239], v[244:247], v[32:47]
	ds_read_b64_tr_b16 v[12:13], v255 offset:16384
	ds_read_b64_tr_b16 v[6:7], v253 offset:16384
	ds_read_b64_tr_b16 v[8:9], v200 offset:16384
	v_mfma_f32_32x32x16_bf16 v[16:31], v[240:243], v[244:247], v[16:31]
	ds_read_b64_tr_b16 v[236:237], v251 offset:20480
	ds_read_b64_tr_b16 v[238:239], v252 offset:20480
	ds_read_b64_tr_b16 v[244:245], v235 offset:20480
	s_waitcnt lgkmcnt(9)
	v_mfma_f32_32x32x16_bf16 v[32:47], v[160:163], v[168:171], v[32:47]
	ds_read_b64_tr_b16 v[246:247], v255 offset:20480
	ds_read_b64_tr_b16 v[240:241], v253 offset:20480
	ds_read_b64_tr_b16 v[242:243], v200 offset:20480
	v_mfma_f32_32x32x16_bf16 v[16:31], v[164:167], v[168:171], v[16:31]
	ds_read_b64_tr_b16 v[160:161], v251 offset:24576
	ds_read_b64_tr_b16 v[162:163], v252 offset:24576
	ds_read_b64_tr_b16 v[168:169], v235 offset:24576
	s_waitcnt lgkmcnt(9)
	v_mfma_f32_32x32x16_bf16 v[32:47], v[2:5], v[10:13], v[32:47]
	ds_read_b64_tr_b16 v[170:171], v255 offset:24576
	ds_read_b64_tr_b16 v[164:165], v253 offset:24576
	ds_read_b64_tr_b16 v[166:167], v200 offset:24576
	v_mfma_f32_32x32x16_bf16 v[16:31], v[6:9], v[10:13], v[16:31]
	ds_read_b64_tr_b16 v[2:3], v251 offset:28672
	ds_read_b64_tr_b16 v[4:5], v252 offset:28672
	ds_read_b64_tr_b16 v[10:11], v235 offset:28672
	s_waitcnt lgkmcnt(9)
	v_mfma_f32_32x32x16_bf16 v[32:47], v[236:239], v[244:247], v[32:47]
	ds_read_b64_tr_b16 v[12:13], v255 offset:28672
	ds_read_b64_tr_b16 v[6:7], v253 offset:28672
	ds_read_b64_tr_b16 v[8:9], v200 offset:28672
	v_mfma_f32_32x32x16_bf16 v[16:31], v[240:243], v[244:247], v[16:31]
	s_waitcnt lgkmcnt(6)
	v_mfma_f32_32x32x16_bf16 v[32:47], v[160:163], v[168:171], v[32:47]
	v_mfma_f32_32x32x16_bf16 v[16:31], v[164:167], v[168:171], v[16:31]
	s_waitcnt lgkmcnt(0)
	v_mfma_f32_32x32x16_bf16 v[32:47], v[2:5], v[10:13], v[32:47]
	v_mfma_f32_32x32x16_bf16 v[16:31], v[6:9], v[10:13], v[16:31]
	s_branch .Lret_d1_end
.Lret_d1_ctx:
	ds_read_b64_tr_b16 v[2:3], v251
	ds_read_b64_tr_b16 v[4:5], v252
	ds_read_b64_tr_b16 v[10:11], v235
	ds_read_b64_tr_b16 v[12:13], v255
	ds_read_b64_tr_b16 v[6:7], v253
	ds_read_b64_tr_b16 v[8:9], v200
	ds_read_b64_tr_b16 v[236:237], v251 offset:4096
	ds_read_b64_tr_b16 v[238:239], v252 offset:4096
	ds_read_b64_tr_b16 v[244:245], v235 offset:4096
	ds_read_b64_tr_b16 v[246:247], v255 offset:4096
	ds_read_b64_tr_b16 v[240:241], v253 offset:4096
	ds_read_b64_tr_b16 v[242:243], v200 offset:4096
	ds_read_b64_tr_b16 v[160:161], v251 offset:8192
	ds_read_b64_tr_b16 v[162:163], v252 offset:8192
	ds_read_b64_tr_b16 v[168:169], v235 offset:8192
	s_waitcnt lgkmcnt(9)
	v_mfma_f32_32x32x16_bf16 v[32:47], v[2:5], v[10:13], v[32:47]
	ds_read_b64_tr_b16 v[170:171], v255 offset:8192
	ds_read_b64_tr_b16 v[164:165], v253 offset:8192
	ds_read_b64_tr_b16 v[166:167], v200 offset:8192
	v_mfma_f32_32x32x16_bf16 v[16:31], v[6:9], v[10:13], v[16:31]
	ds_read_b64_tr_b16 v[2:3], v251 offset:12288
	ds_read_b64_tr_b16 v[4:5], v252 offset:12288
	ds_read_b64_tr_b16 v[10:11], v235 offset:12288
	s_waitcnt lgkmcnt(9)
	v_mfma_f32_32x32x16_bf16 v[32:47], v[236:239], v[244:247], v[32:47]
	ds_read_b64_tr_b16 v[12:13], v255 offset:12288
	ds_read_b64_tr_b16 v[6:7], v253 offset:12288
	ds_read_b64_tr_b16 v[8:9], v200 offset:12288
	v_mfma_f32_32x32x16_bf16 v[16:31], v[240:243], v[244:247], v[16:31]
	ds_read_b64_tr_b16 v[236:237], v251 offset:16384
	ds_read_b64_tr_b16 v[238:239], v252 offset:16384
	ds_read_b64_tr_b16 v[244:245], v235 offset:16384
	s_waitcnt lgkmcnt(9)
	v_mfma_f32_32x32x16_bf16 v[32:47], v[160:163], v[168:171], v[32:47]
	ds_read_b64_tr_b16 v[246:247], v255 offset:16384
	ds_read_b64_tr_b16 v[240:241], v253 offset:16384
	ds_read_b64_tr_b16 v[242:243], v200 offset:16384
	v_mfma_f32_32x32x16_bf16 v[16:31], v[164:167], v[168:171], v[16:31]
	ds_read_b64_tr_b16 v[160:161], v251 offset:20480
	ds_read_b64_tr_b16 v[162:163], v252 offset:20480
	ds_read_b64_tr_b16 v[168:169], v235 offset:20480
	s_waitcnt lgkmcnt(9)
	v_mfma_f32_32x32x16_bf16 v[32:47], v[2:5], v[10:13], v[32:47]
	ds_read_b64_tr_b16 v[170:171], v255 offset:20480
	ds_read_b64_tr_b16 v[164:165], v253 offset:20480
	ds_read_b64_tr_b16 v[166:167], v200 offset:20480
	v_mfma_f32_32x32x16_bf16 v[16:31], v[6:9], v[10:13], v[16:31]
	ds_read_b64_tr_b16 v[2:3], v251 offset:24576
	ds_read_b64_tr_b16 v[4:5], v252 offset:24576
	ds_read_b64_tr_b16 v[10:11], v235 offset:24576
	s_waitcnt lgkmcnt(9)
	v_mfma_f32_32x32x16_bf16 v[32:47], v[236:239], v[244:247], v[32:47]
	ds_read_b64_tr_b16 v[12:13], v255 offset:24576
	ds_read_b64_tr_b16 v[6:7], v253 offset:24576
	ds_read_b64_tr_b16 v[8:9], v200 offset:24576
	v_mfma_f32_32x32x16_bf16 v[16:31], v[240:243], v[244:247], v[16:31]
	ds_read_b64_tr_b16 v[236:237], v251 offset:28672
	ds_read_b64_tr_b16 v[238:239], v252 offset:28672
	ds_read_b64_tr_b16 v[244:245], v235 offset:28672
	s_waitcnt lgkmcnt(9)
	v_mfma_f32_32x32x16_bf16 v[32:47], v[160:163], v[168:171], v[32:47]
	ds_read_b64_tr_b16 v[246:247], v255 offset:28672
	ds_read_b64_tr_b16 v[240:241], v253 offset:28672
	ds_read_b64_tr_b16 v[242:243], v200 offset:28672
	v_mfma_f32_32x32x16_bf16 v[16:31], v[164:167], v[168:171], v[16:31]
	s_waitcnt lgkmcnt(6)
	v_mfma_f32_32x32x16_bf16 v[32:47], v[2:5], v[10:13], v[32:47]
	v_mfma_f32_32x32x16_bf16 v[16:31], v[6:9], v[10:13], v[16:31]
	s_waitcnt lgkmcnt(0)
	v_mfma_f32_32x32x16_bf16 v[32:47], v[236:239], v[244:247], v[32:47]
	v_mfma_f32_32x32x16_bf16 v[16:31], v[240:243], v[244:247], v[16:31]
	s_branch .Lret_d1_end
.LBB0_949:
	v_mad_u64_u32 v[2:3], s[18:19], v197, s68, v[192:193]
	s_waitcnt vmcnt(4)
	ds_write_b128 v2, v[156:159]
	s_waitcnt vmcnt(3)
	ds_write_b128 v2, v[152:155] offset:8704
	ds_write_b128 v249, v[184:187] offset:34816
	s_waitcnt vmcnt(2)
	ds_write_b128 v249, v[188:191] offset:43008
	ds_write_b128 v2, v[148:151] offset:17408
	s_waitcnt vmcnt(1)
	ds_write_b128 v2, v[144:147] offset:26112
	s_cbranch_execnz .LBB0_929
.LBB0_950:
	s_waitcnt vmcnt(3)
	ds_write_b128 v249, v[184:187] offset:34816
	s_waitcnt vmcnt(2)
	ds_write_b128 v249, v[188:191] offset:43008
	s_and_b64 vcc, exec, s[16:17]
	s_waitcnt vmcnt(1)
	ds_write_b128 v249, v[180:183] offset:51200
	s_waitcnt vmcnt(0)
	ds_write_b128 v249, v[176:179] offset:59392
	s_cbranch_vccz .LBB0_930
	s_branch .LBB0_931

.LBB0_974:
	v_readfirstlane_b32 s16, v207
	s_cmp_eq_u32 s16, 0
	s_cbranch_scc0 .Lret_f_dg1
	ds_read_b64_tr_b16 v[2:3], v235
	ds_read_b64_tr_b16 v[4:5], v255
	ds_read_b128 v[6:9], v195
	ds_read_b128 v[10:13], v195 offset:8704
	ds_read_b64_tr_b16 v[236:237], v235 offset:4096
	ds_read_b64_tr_b16 v[238:239], v255 offset:4096
	ds_read_b128 v[240:243], v195 offset:32
	ds_read_b128 v[244:247], v195 offset:8736
	ds_read_b64_tr_b16 v[112:113], v235 offset:8192
	ds_read_b64_tr_b16 v[114:115], v255 offset:8192
	s_waitcnt lgkmcnt(6)
	v_mfma_f32_32x32x16_bf16 v[96:111], v[2:5], v[6:9], v[96:111]
	ds_read_b128 v[120:123], v195 offset:8768
	v_mfma_f32_32x32x16_bf16 v[80:95], v[2:5], v[10:13], v[80:95]
	ds_read_b64_tr_b16 v[2:3], v235 offset:12288
	ds_read_b64_tr_b16 v[4:5], v255 offset:12288
	s_waitcnt lgkmcnt(5)
	v_mfma_f32_32x32x16_bf16 v[96:111], v[236:239], v[240:243], v[96:111]
	ds_read_b128 v[10:13], v195 offset:8800
	v_mfma_f32_32x32x16_bf16 v[80:95], v[236:239], v[244:247], v[80:95]
	s_waitcnt lgkmcnt(3)
	v_mfma_f32_32x32x16_bf16 v[80:95], v[112:115], v[120:123], v[80:95]
	s_waitcnt lgkmcnt(0)
	v_mfma_f32_32x32x16_bf16 v[80:95], v[2:5], v[10:13], v[80:95]
	s_branch .Lret_f_end
.Lret_f_dg1:
	ds_read_b64_tr_b16 v[2:3], v235
	ds_read_b64_tr_b16 v[4:5], v255
	ds_read_b128 v[6:9], v195
	ds_read_b128 v[10:13], v195 offset:8704
	ds_read_b64_tr_b16 v[236:237], v235 offset:4096
	ds_read_b64_tr_b16 v[238:239], v255 offset:4096
	ds_read_b128 v[240:243], v195 offset:32
	ds_read_b128 v[244:247], v195 offset:8736
	ds_read_b64_tr_b16 v[112:113], v235 offset:8192
	ds_read_b64_tr_b16 v[114:115], v255 offset:8192
	s_waitcnt lgkmcnt(6)
	v_mfma_f32_32x32x16_bf16 v[96:111], v[2:5], v[6:9], v[96:111]
	ds_read_b128 v[116:119], v195 offset:64
	ds_read_b128 v[120:123], v195 offset:8768
	v_mfma_f32_32x32x16_bf16 v[80:95], v[2:5], v[10:13], v[80:95]
	ds_read_b64_tr_b16 v[2:3], v235 offset:12288
	ds_read_b64_tr_b16 v[4:5], v255 offset:12288
	s_waitcnt lgkmcnt(6)
	v_mfma_f32_32x32x16_bf16 v[96:111], v[236:239], v[240:243], v[96:111]
	ds_read_b128 v[6:9], v195 offset:96
	ds_read_b128 v[10:13], v195 offset:8800
	v_mfma_f32_32x32x16_bf16 v[80:95], v[236:239], v[244:247], v[80:95]
	ds_read_b64_tr_b16 v[236:237], v235 offset:16384
	ds_read_b64_tr_b16 v[238:239], v255 offset:16384
	s_waitcnt lgkmcnt(6)
	v_mfma_f32_32x32x16_bf16 v[96:111], v[112:115], v[116:119], v[96:111]
	ds_read_b128 v[240:243], v195 offset:128
	ds_read_b128 v[244:247], v195 offset:8832
	v_mfma_f32_32x32x16_bf16 v[80:95], v[112:115], v[120:123], v[80:95]
	ds_read_b64_tr_b16 v[112:113], v235 offset:20480
	ds_read_b64_tr_b16 v[114:115], v255 offset:20480
	s_waitcnt lgkmcnt(6)
	v_mfma_f32_32x32x16_bf16 v[96:111], v[2:5], v[6:9], v[96:111]
	ds_read_b128 v[116:119], v195 offset:160
	ds_read_b128 v[120:123], v195 offset:8864
	v_mfma_f32_32x32x16_bf16 v[80:95], v[2:5], v[10:13], v[80:95]
	ds_read_b64_tr_b16 v[2:3], v235 offset:24576
	ds_read_b64_tr_b16 v[4:5], v255 offset:24576
	s_waitcnt lgkmcnt(6)
	v_mfma_f32_32x32x16_bf16 v[96:111], v[236:239], v[240:243], v[96:111]
	ds_read_b128 v[10:13], v195 offset:8896
	v_mfma_f32_32x32x16_bf16 v[80:95], v[236:239], v[244:247], v[80:95]
	ds_read_b64_tr_b16 v[236:237], v235 offset:28672
	ds_read_b64_tr_b16 v[238:239], v255 offset:28672
	s_waitcnt lgkmcnt(5)
	v_mfma_f32_32x32x16_bf16 v[96:111], v[112:115], v[116:119], v[96:111]
	ds_read_b128 v[244:247], v195 offset:8928
	v_mfma_f32_32x32x16_bf16 v[80:95], v[112:115], v[120:123], v[80:95]
	s_waitcnt lgkmcnt(3)
	v_mfma_f32_32x32x16_bf16 v[80:95], v[2:5], v[10:13], v[80:95]
	s_waitcnt lgkmcnt(0)
	v_mfma_f32_32x32x16_bf16 v[80:95], v[236:239], v[244:247], v[80:95]
.Lret_f_end:
	s_nop 3
	v_add_u32_e32 v1, v234, v207
	v_add_u32_e32 v10, 1, v1
	v_cvt_f32_i32_e32 v14, v10
	v_mul_f32_e32 v2, v232, v14
	v_exp_f32_e32 v4, v2
	v_lshlrev_b32_e32 v2, 3, v233
	v_mul_lo_u32 v3, v1, s68
	v_add3_u32 v5, v208, v2, v3
	v_mul_f32_e32 v2, v4, v96
	v_mul_f32_e32 v3, v4, v97
	v_cvt_pk_bf16_f32 v2, v2, v3
	v_mul_f32_e32 v3, v4, v98
	v_mul_f32_e32 v6, v4, v99
	v_cvt_pk_bf16_f32 v3, v3, v6
	v_add_u32_e32 v1, 33, v1
	ds_write_b64 v5, v[2:3] offset:34816
	v_mul_f32_e32 v2, v4, v100
	v_mul_f32_e32 v3, v4, v101
	v_cvt_f32_i32_e32 v1, v1
	v_cvt_pk_bf16_f32 v2, v2, v3
	v_mul_f32_e32 v3, v4, v102
	v_mul_f32_e32 v6, v4, v103
	v_cvt_pk_bf16_f32 v3, v3, v6
	ds_write_b64 v5, v[2:3] offset:34832
	v_mul_f32_e32 v2, v4, v104
	v_mul_f32_e32 v3, v4, v105
	v_cvt_pk_bf16_f32 v2, v2, v3
	v_mul_f32_e32 v3, v4, v106
	v_mul_f32_e32 v1, v232, v1
	v_mul_f32_e32 v6, v4, v107
	v_cvt_pk_bf16_f32 v3, v3, v6
	v_exp_f32_e32 v1, v1
	ds_write_b64 v5, v[2:3] offset:34848
	v_mul_f32_e32 v2, v4, v108
	v_mul_f32_e32 v3, v4, v109
	v_cvt_pk_bf16_f32 v2, v2, v3
	v_mul_f32_e32 v3, v4, v110
	v_mul_f32_e32 v4, v4, v111
	v_cvt_pk_bf16_f32 v3, v3, v4
	ds_write_b64 v5, v[2:3] offset:34864
	v_mul_f32_e32 v2, v1, v80
	v_mul_f32_e32 v3, v1, v81
	v_cvt_pk_bf16_f32 v2, v2, v3
	v_mul_f32_e32 v3, v1, v82
	v_mul_f32_e32 v4, v1, v83
	v_cvt_pk_bf16_f32 v3, v3, v4
	ds_write_b64 v5, v[2:3] offset:43520
	v_mul_f32_e32 v2, v1, v84
	v_mul_f32_e32 v3, v1, v85
	v_cvt_pk_bf16_f32 v2, v2, v3
	v_mul_f32_e32 v3, v1, v86
	v_mul_f32_e32 v4, v1, v87
	v_cvt_pk_bf16_f32 v3, v3, v4
	ds_write_b64 v5, v[2:3] offset:43536
	v_mul_f32_e32 v2, v1, v88
	v_mul_f32_e32 v3, v1, v89
	v_cvt_pk_bf16_f32 v2, v2, v3
	v_mul_f32_e32 v3, v1, v90
	s_add_u32 s16, s40, s28
	v_mul_f32_e32 v4, v1, v91
	v_cvt_pk_bf16_f32 v3, v3, v4
	s_addc_u32 s17, s41, s34
	ds_write_b64 v5, v[2:3] offset:43552
	v_mul_f32_e32 v2, v1, v92
	v_mul_f32_e32 v3, v1, v93
	s_lshl_b64 s[18:19], s[16:17], 12
	v_cvt_pk_bf16_f32 v2, v2, v3
	v_mul_f32_e32 v3, v1, v94
	s_or_b32 s18, s18, s80
	v_mul_f32_e32 v1, v1, v95
	v_cvt_pk_bf16_f32 v3, v3, v1
	s_add_u32 s56, s26, s18
	ds_write_b64 v5, v[2:3] offset:43568
	s_waitcnt lgkmcnt(0)
	s_barrier
	s_addc_u32 s57, s27, s19
	v_sub_u32_e32 v10, 0x7f, v197
	ds_read_b128 v[2:5], v228 offset:34816
	s_add_u32 s54, s64, s18
	v_cndmask_b32_e64 v1, v10, v197, s[44:45]
	s_addc_u32 s55, s65, s19
	s_lshl_b64 s[16:17], s[16:17], 5
	v_lshl_or_b32 v8, v1, 11, v203
	s_add_u32 s18, s78, s16
	v_ashrrev_i32_e32 v9, 31, v8
	s_addc_u32 s19, s79, s17
	v_lshl_add_u64 v[6:7], v[8:9], 1, s[56:57]
	s_mov_b64 s[16:17], -1
	s_and_b64 vcc, exec, s[46:47]
	v_mbcnt_hi_u32_b32 v1, -1, v226
	s_cbranch_vccz .LBB0_982
	global_load_dwordx4 v[12:15], v[6:7], off
	s_waitcnt lgkmcnt(0)
	v_lshlrev_b32_e32 v11, 16, v2
	v_and_b32_e32 v80, 0xffff0000, v2
	v_lshlrev_b32_e32 v81, 16, v3
	v_and_b32_e32 v82, 0xffff0000, v3
	v_lshlrev_b32_e32 v83, 16, v4
	v_and_b32_e32 v84, 0xffff0000, v4
	v_lshlrev_b32_e32 v85, 16, v5
	v_and_b32_e32 v86, 0xffff0000, v5
	v_and_b32_e32 v87, 64, v1
	v_xor_b32_e32 v88, 1, v1
	v_add_u32_e32 v87, 64, v87
	v_cmp_lt_i32_e32 vcc, v88, v87
	v_xor_b32_e32 v89, 2, v1
	v_xor_b32_e32 v90, 4, v1
	v_cndmask_b32_e32 v88, v1, v88, vcc
	v_lshlrev_b32_e32 v88, 2, v88
	v_cmp_lt_i32_e32 vcc, v89, v87
	v_xor_b32_e32 v91, 8, v1
	v_lshl_add_u64 v[8:9], v[8:9], 1, s[54:55]
	v_cndmask_b32_e32 v89, v1, v89, vcc
	v_lshlrev_b32_e32 v89, 2, v89
	v_cmp_lt_i32_e32 vcc, v90, v87
	s_waitcnt vmcnt(0)
	v_lshlrev_b32_e32 v92, 16, v12
	v_and_b32_e32 v12, 0xffff0000, v12
	v_lshlrev_b32_e32 v93, 16, v13
	v_and_b32_e32 v13, 0xffff0000, v13
	v_lshlrev_b32_e32 v94, 16, v14
	v_and_b32_e32 v14, 0xffff0000, v14
	v_lshlrev_b32_e32 v95, 16, v15
	v_and_b32_e32 v15, 0xffff0000, v15
	v_add_f32_e32 v11, v92, v11
	v_add_f32_e32 v12, v12, v80
	v_add_f32_e32 v81, v93, v81
	v_add_f32_e32 v13, v13, v82
	v_add_f32_e32 v82, v94, v83
	v_add_f32_e32 v83, v14, v84
	v_add_f32_e32 v84, v95, v85
	v_add_f32_e32 v15, v15, v86
	v_add_f32_e32 v14, v84, v15
	v_add_f32_e32 v80, v82, v83
	v_add_f32_e32 v85, v81, v13
	v_add_f32_e32 v86, v11, v12
	v_mul_f32_e32 v92, v84, v84
	v_mul_f32_e32 v93, v82, v82
	v_mul_f32_e32 v94, v81, v81
	v_mul_f32_e32 v95, v11, v11
	v_add_f32_e32 v14, v80, v14
	v_add_f32_e32 v80, v86, v85
	v_fmac_f32_e32 v92, v15, v15
	v_fmac_f32_e32 v93, v83, v83
	v_fmac_f32_e32 v94, v13, v13
	v_fmac_f32_e32 v95, v12, v12
	v_add_f32_e32 v14, v80, v14
	v_add_f32_e32 v80, v93, v92
	v_add_f32_e32 v85, v95, v94
	v_add_f32_e32 v80, v85, v80
	ds_bpermute_b32 v85, v88, v14
	ds_bpermute_b32 v86, v88, v80
	v_cndmask_b32_e32 v88, v1, v90, vcc
	v_lshlrev_b32_e32 v88, 2, v88
	v_cmp_lt_i32_e32 vcc, v91, v87
	s_waitcnt lgkmcnt(1)
	v_add_f32_e32 v14, v14, v85
	s_waitcnt lgkmcnt(0)
	v_add_f32_e32 v80, v80, v86
	ds_bpermute_b32 v85, v89, v14
	ds_bpermute_b32 v86, v89, v80
	v_cndmask_b32_e32 v87, v1, v91, vcc
	v_lshlrev_b32_e32 v87, 2, v87
	s_waitcnt lgkmcnt(1)
	v_add_f32_e32 v14, v14, v85
	s_waitcnt lgkmcnt(0)
	v_add_f32_e32 v85, v80, v86
	ds_bpermute_b32 v86, v88, v14
	ds_bpermute_b32 v88, v88, v85
	v_cvt_pk_bf16_f32 v80, v11, v12
	v_cvt_pk_bf16_f32 v81, v81, v13
	v_cvt_pk_bf16_f32 v82, v82, v83
	s_waitcnt lgkmcnt(1)
	v_add_f32_e32 v11, v14, v86
	s_waitcnt lgkmcnt(0)
	v_add_f32_e32 v12, v85, v88
	ds_bpermute_b32 v13, v87, v11
	ds_bpermute_b32 v14, v87, v12
	v_cvt_pk_bf16_f32 v83, v84, v15
	global_store_dwordx4 v[8:9], v[80:83], off
	s_and_saveexec_b64 s[16:17], s[8:9]
	s_cbranch_execz .LBB0_981
	v_lshlrev_b32_e32 v8, 3, v10
	v_ashrrev_i32_e32 v9, 31, v8
	v_lshl_add_u64 v[8:9], v[8:9], 2, s[18:19]
	s_waitcnt lgkmcnt(1)
	v_add_f32_e32 v10, v11, v13
	s_waitcnt lgkmcnt(0)
	v_add_f32_e32 v11, v12, v14
	global_atomic_add_f32 v[8:9], v10, off
	global_atomic_add_f32 v[8:9], v11, off offset:4
